# write-through (sc1) stores in both norm phases N1/N2 so the barrier's L2 write-back finds less dirty data
# speedup vs baseline: 1.0009x; 1.0009x over previous
;     __device__ __forceinline__ const float* in(int i) const { return (const float*)(const __attribute__((address_space(1))) float*)ld(i); }
;     __device__ __forceinline__ unsigned char* ws() const { return (unsigned char*)(__attribute__((address_space(1))) unsigned char*)ld(23); }
; __device__ __forceinline__ unsigned pk2(float lo, float hi) { return cvtpk(lo, hi); }
; #define LDS_WAIT() asm volatile("s_waitcnt lgkmcnt(0)" ::: "memory")
; template <bool UPMAP>
; __device__ __forceinline__ void transpose_item(const float* W, int K, int N, bf16* WT, float* scr, int item, int lane) {
;     const int nblk = N / 32, kb = item / nblk, nb = item % nblk, k0 = 64 * kb, n0 = 32 * nb;
;     { f32x4 v[8];
; #pragma unroll
;       for (int i = 0; i < 8; ++i) v[i] = *(const f32x4*)(W + (size_t)(k0 + 8 * i + (lane >> 3)) * N + n0 + 4 * (lane & 7));
; #pragma unroll
;       for (int i = 0; i < 8; ++i) { float* d = scr + (8 * i + (lane >> 3)) * 33 + 4 * (lane & 7); d[0] = v[i][0]; d[1] = v[i][1]; d[2] = v[i][2]; d[3] = v[i][3]; } }
;     LDS_WAIT();
;     const int c = lane & 7;
; #pragma unroll
;     for (int j = 0; j < 4; ++j) { const int n = (lane >> 3) + 8 * j; const float* s = scr + (8 * c) * 33 + n;
;         v4u o; o.x = pk2(s[0 * 33], s[1 * 33]); o.y = pk2(s[2 * 33], s[3 * 33]); o.z = pk2(s[4 * 33], s[5 * 33]); o.w = pk2(s[6 * 33], s[7 * 33]);
;         const int nsrc = n0 + n; int nrow = nsrc;
;         if (UPMAP) { const int bj = nsrc / 2816, chn = nsrc - bj * 2816; nrow = (chn >> 7) * 256 + bj * 128 + (chn & 127); }
;         *(v4u*)(WT + (size_t)nrow * K + k0 + 8 * c) = o; }
;     LDS_WAIT();
; template <int PART>
; __device__ __forceinline__ void prologue(const KPD& kp, unsigned char* lds, int tid, int lane, int wave) {
;     ...
;         transpose_item<false>(kp.in(I_WDOWN) + (size_t)l * DFF * D, DFF, D, (bf16*)(ws + WS_WDN) + (size_t)l * D * DFF, scr, r, lane);
.LBB0_90:
	s_mul_hi_i32 s2, s17, 0x5ac5242b
	s_lshr_b32 s3, s2, 31
	s_ashr_i32 s2, s2, 11
	s_add_i32 s2, s2, s3
	s_mul_i32 s3, s2, 0xffffe970
	s_add_i32 s18, s17, s3
	s_cmpk_gt_i32 s18, 0x40f
	s_mov_b64 s[4:5], -1
	s_cbranch_scc0 .LBB0_100
	s_cmpk_gt_u32 s18, 0x60f
	s_cbranch_scc0 .LBB0_97
	s_cmpk_gt_u32 s18, 0x110f
	s_cbranch_scc0 .LBB0_94
	v_mov_b32_e32 v26, 0x264a8
	ds_read_b64 v[26:27], v26
	s_mul_i32 s4, s2, 0xb00000
	s_mul_hi_i32 s3, s2, 0xb00000
	s_mul_hi_i32 s5, s2, 0x580000
	v_lshlrev_b32_e32 v34, 2, v2
	s_waitcnt lgkmcnt(0)
	v_readfirstlane_b32 s20, v26
	v_readfirstlane_b32 s19, v27
	s_add_u32 s4, s20, s4
	s_addc_u32 s19, s19, s3
	s_mul_i32 s3, s2, 0x580000
	s_add_u32 s20, s6, s3
	s_addc_u32 s21, s7, s5
	s_add_i32 s3, s18, 0xeef0
	s_bfe_u32 s22, s3, 0xb0005
	s_lshl_b32 s3, s3, 5
	s_and_b32 s3, s3, 0x3e0
	s_lshl_b32 s5, s3, 2
	s_add_u32 s4, s4, s5
	s_addc_u32 s5, s19, 0
	v_lshl_add_u64 v[26:27], s[4:5], 0, v[34:35]
	v_lshl_or_b32 v34, s22, 18, v10
	v_lshl_add_u64 v[36:37], v[26:27], 0, v[34:35]
	s_mov_b32 s4, 0x8000
	v_add_co_u32_e32 v30, vcc, s4, v36
	s_mov_b32 s4, 0x10000
	s_nop 0
	v_addc_co_u32_e32 v31, vcc, 0, v37, vcc
	v_add_co_u32_e32 v42, vcc, s4, v36
	s_mov_b32 s4, 0x18000
	s_nop 0
	v_addc_co_u32_e32 v43, vcc, 0, v37, vcc
	v_add_co_u32_e32 v46, vcc, s4, v36
	s_mov_b32 s4, 0x20000
	s_nop 0
	v_addc_co_u32_e32 v47, vcc, 0, v37, vcc
	v_add_co_u32_e32 v50, vcc, s4, v36
	s_mov_b32 s4, 0x28000
	s_nop 0
	v_addc_co_u32_e32 v51, vcc, 0, v37, vcc
	v_add_co_u32_e32 v54, vcc, s4, v36
	global_load_dwordx4 v[26:29], v[36:37], off
	s_nop 0
	global_load_dwordx4 v[30:33], v[30:31], off
	v_addc_co_u32_e32 v55, vcc, 0, v37, vcc
	global_load_dwordx4 v[42:45], v[42:43], off
	s_nop 0
	global_load_dwordx4 v[46:49], v[46:47], off
	s_nop 0
	global_load_dwordx4 v[50:53], v[50:51], off
	s_nop 0
	global_load_dwordx4 v[54:57], v[54:55], off
	s_mov_b32 s4, 0x30000
	v_add_co_u32_e32 v58, vcc, s4, v36
	s_mov_b32 s4, 0x38000
	s_nop 0
	v_addc_co_u32_e32 v59, vcc, 0, v37, vcc
	global_load_dwordx4 v[58:61], v[58:59], off
	v_add_co_u32_e32 v36, vcc, s4, v36
	s_lshl_b32 s4, s22, 7
	s_nop 0
	v_addc_co_u32_e32 v37, vcc, 0, v37, vcc
	global_load_dwordx4 v[62:65], v[36:37], off
	v_or_b32_e32 v34, s3, v5
	s_add_u32 s4, s20, s4
	v_or_b32_e32 v36, s3, v6
	v_mul_u32_u24_e32 v38, 0xb00, v34
	s_addc_u32 s5, s21, 0
	v_lshlrev_b32_e32 v34, 1, v4
	v_mul_u32_u24_e32 v39, 0xb00, v36
	v_lshl_add_u64 v[36:37], s[4:5], 0, v[34:35]
	v_lshlrev_b32_e32 v34, 1, v38
	v_lshl_add_u64 v[66:67], v[36:37], 0, v[34:35]
	v_lshlrev_b32_e32 v34, 1, v39
	v_lshl_add_u64 v[68:69], v[36:37], 0, v[34:35]
	s_mov_b64 s[4:5], 0
	s_waitcnt vmcnt(7)
	ds_write2_b32 v11, v26, v27 offset1:1
	ds_write2_b32 v11, v28, v29 offset0:2 offset1:3
	s_waitcnt vmcnt(6)
	ds_write2_b32 v12, v30, v31 offset1:1
	ds_write2_b32 v13, v32, v33 offset1:1
	s_waitcnt vmcnt(5)
	ds_write2_b32 v14, v42, v43 offset1:1
	ds_write2_b32 v15, v44, v45 offset1:1
	s_waitcnt vmcnt(4)
	ds_write2_b32 v16, v46, v47 offset1:1
	ds_write2_b32 v17, v48, v49 offset1:1
	s_waitcnt vmcnt(3)
	ds_write2_b32 v18, v50, v51 offset1:1
	ds_write2_b32 v19, v52, v53 offset1:1
	s_waitcnt vmcnt(2)
	ds_write2_b32 v20, v54, v55 offset1:1
	ds_write2_b32 v21, v56, v57 offset1:1
	s_waitcnt vmcnt(1)
	ds_write2_b32 v22, v58, v59 offset1:1
	ds_write2_b32 v23, v60, v61 offset1:1
	s_waitcnt vmcnt(0)
	ds_write2_b32 v24, v62, v63 offset1:1
	ds_write2_b32 v25, v64, v65 offset1:1
	s_waitcnt lgkmcnt(0)
	ds_read2_b32 v[30:31], v9 offset0:33 offset1:41
	ds_read2_b32 v[32:33], v9 offset1:8
	ds_read2_b32 v[42:43], v9 offset0:66 offset1:74
	ds_read2_b32 v[44:45], v9 offset0:99 offset1:107
	ds_read2_b32 v[46:47], v9 offset0:132 offset1:140
	ds_read2_b32 v[48:49], v9 offset0:165 offset1:173
	ds_read2_b32 v[50:51], v9 offset0:198 offset1:206
	ds_read2_b32 v[52:53], v9 offset0:231 offset1:239
	ds_read2_b32 v[54:55], v9 offset0:16 offset1:24
	ds_read2_b32 v[56:57], v9 offset0:49 offset1:57
	s_waitcnt lgkmcnt(8)
	v_cvt_pk_bf16_f32 v26, v32, v30
	s_waitcnt lgkmcnt(6)
	v_cvt_pk_bf16_f32 v27, v42, v44
	s_waitcnt lgkmcnt(4)
	v_cvt_pk_bf16_f32 v28, v46, v48
	s_waitcnt lgkmcnt(2)
	v_cvt_pk_bf16_f32 v29, v50, v52
	global_store_dwordx4 v[66:67], v[26:29], off sc1
	v_cvt_pk_bf16_f32 v30, v33, v31
	v_cvt_pk_bf16_f32 v31, v43, v45
	v_cvt_pk_bf16_f32 v32, v47, v49
	v_cvt_pk_bf16_f32 v33, v51, v53
	ds_read2_b32 v[42:43], v9 offset0:82 offset1:90
	ds_read2_b32 v[44:45], v9 offset0:115 offset1:123
	ds_read2_b32 v[46:47], v9 offset0:148 offset1:156
	ds_read2_b32 v[48:49], v9 offset0:181 offset1:189
	ds_read2_b32 v[50:51], v9 offset0:214 offset1:222
	ds_read2_b32 v[52:53], v9 offset0:247 offset1:255
	global_store_dwordx4 v[68:69], v[30:33], off sc1
	s_waitcnt lgkmcnt(6)
	v_cvt_pk_bf16_f32 v26, v54, v56
	s_waitcnt lgkmcnt(4)
	v_cvt_pk_bf16_f32 v27, v42, v44
	s_waitcnt lgkmcnt(2)
	v_cvt_pk_bf16_f32 v28, v46, v48
	s_waitcnt lgkmcnt(0)
	v_cvt_pk_bf16_f32 v29, v50, v52
	v_or_b32_e32 v30, s3, v7
	v_mul_u32_u24_e32 v30, 0xb00, v30
	v_lshlrev_b32_e32 v34, 1, v30
	v_lshl_add_u64 v[30:31], v[36:37], 0, v[34:35]
	global_store_dwordx4 v[30:31], v[26:29], off sc1
	v_or_b32_e32 v30, s3, v8
	v_mul_u32_u24_e32 v30, 0xb00, v30
	v_lshlrev_b32_e32 v34, 1, v30
	v_lshl_add_u64 v[30:31], v[36:37], 0, v[34:35]
	v_cvt_pk_bf16_f32 v26, v55, v57
	v_cvt_pk_bf16_f32 v27, v43, v45
	v_cvt_pk_bf16_f32 v28, v47, v49
	v_cvt_pk_bf16_f32 v29, v51, v53
	global_store_dwordx4 v[30:31], v[26:29], off sc1
	s_waitcnt lgkmcnt(0)
;     __device__ __forceinline__ const float* in(int i) const { return (const float*)(const __attribute__((address_space(1))) float*)ld(i); }
;     __device__ __forceinline__ unsigned char* ws() const { return (unsigned char*)(__attribute__((address_space(1))) unsigned char*)ld(23); }
; __device__ __forceinline__ unsigned pk2(float lo, float hi) { return cvtpk(lo, hi); }
; #define LDS_WAIT() asm volatile("s_waitcnt lgkmcnt(0)" ::: "memory")
; template <bool UPMAP>
; __device__ __forceinline__ void transpose_item(const float* W, int K, int N, bf16* WT, float* scr, int item, int lane) {
;     const int nblk = N / 32, kb = item / nblk, nb = item % nblk, k0 = 64 * kb, n0 = 32 * nb;
;     { f32x4 v[8];
; #pragma unroll
;       for (int i = 0; i < 8; ++i) v[i] = *(const f32x4*)(W + (size_t)(k0 + 8 * i + (lane >> 3)) * N + n0 + 4 * (lane & 7));
; #pragma unroll
;       for (int i = 0; i < 8; ++i) { float* d = scr + (8 * i + (lane >> 3)) * 33 + 4 * (lane & 7); d[0] = v[i][0]; d[1] = v[i][1]; d[2] = v[i][2]; d[3] = v[i][3]; } }
;     LDS_WAIT();
;     const int c = lane & 7;
; #pragma unroll
;     for (int j = 0; j < 4; ++j) { const int n = (lane >> 3) + 8 * j; const float* s = scr + (8 * c) * 33 + n;
;         v4u o; o.x = pk2(s[0 * 33], s[1 * 33]); o.y = pk2(s[2 * 33], s[3 * 33]); o.z = pk2(s[4 * 33], s[5 * 33]); o.w = pk2(s[6 * 33], s[7 * 33]);
;         const int nsrc = n0 + n; int nrow = nsrc;
;         if (UPMAP) { const int bj = nsrc / 2816, chn = nsrc - bj * 2816; nrow = (chn >> 7) * 256 + bj * 128 + (chn & 127); }
;         *(v4u*)(WT + (size_t)nrow * K + k0 + 8 * c) = o; }
;     LDS_WAIT();
; template <int PART>
; __device__ __forceinline__ void prologue(const KPD& kp, unsigned char* lds, int tid, int lane, int wave) {
;     ...
;         if (r < I_UP) { transpose_item<true>(kp.in(I_WUP) + (size_t)l * D * DFF2, D, DFF2, (bf16*)(ws + WS_WUP) + (size_t)l * DFF2 * D, scr, r, lane); continue; } r -= I_UP;
.LBB0_94:
	s_andn2_b64 vcc, exec, s[4:5]
	s_cbranch_vccnz .LBB0_96
	v_mov_b32_e32 v26, 0x26490
	ds_read_b64 v[26:27], v26
	s_mul_i32 s4, s2, 0x1600000
	s_mul_hi_i32 s3, s2, 0x1600000
	s_mul_hi_i32 s5, s2, 0xb00000
	v_lshlrev_b32_e32 v34, 2, v2
	s_waitcnt lgkmcnt(0)
	v_readfirstlane_b32 s20, v26
	v_readfirstlane_b32 s19, v27
	s_add_u32 s4, s20, s4
	s_addc_u32 s3, s19, s3
	s_mul_i32 s19, s2, 0xb00000
	s_add_u32 s19, s9, s19
	s_addc_u32 s20, s10, s5
	s_add_i32 s5, s18, 0xf9f0
	s_and_b32 s21, s5, 0xffff
	s_mul_i32 s21, s21, 0xba2f
	s_lshr_b32 s21, s21, 23
	s_mul_i32 s22, s21, 0xb0
	s_sub_i32 s22, s5, s22
	s_lshl_b32 s23, s22, 5
	s_and_b32 s24, s23, 0xffe0
	s_lshl_b32 s5, s24, 2
	v_lshl_or_b32 v28, s21, 6, v5
	s_add_u32 s4, s4, s5
	s_addc_u32 s5, s3, 0
	v_mul_u32_u24_e32 v28, 0x1600, v28
	v_lshl_add_u64 v[26:27], s[4:5], 0, v[34:35]
	v_lshlrev_b32_e32 v34, 2, v28
	v_lshl_add_u64 v[36:37], v[26:27], 0, v[34:35]
	s_mov_b32 s3, 0x2c000
	v_add_co_u32_e32 v30, vcc, s3, v36
	s_mov_b32 s3, 0x58000
	s_nop 0
	v_addc_co_u32_e32 v31, vcc, 0, v37, vcc
	v_add_co_u32_e32 v42, vcc, s3, v36
	s_mov_b32 s3, 0x84000
	s_nop 0
	v_addc_co_u32_e32 v43, vcc, 0, v37, vcc
	v_add_co_u32_e32 v46, vcc, s3, v36
	s_mov_b32 s3, 0xb0000
	s_nop 0
	v_addc_co_u32_e32 v47, vcc, 0, v37, vcc
	v_add_co_u32_e32 v50, vcc, s3, v36
	s_mov_b32 s3, 0xdc000
	s_nop 0
	v_addc_co_u32_e32 v51, vcc, 0, v37, vcc
	v_add_co_u32_e32 v54, vcc, s3, v36
	global_load_dwordx4 v[26:29], v[36:37], off
	s_nop 0
	global_load_dwordx4 v[30:33], v[30:31], off
	v_addc_co_u32_e32 v55, vcc, 0, v37, vcc
	global_load_dwordx4 v[42:45], v[42:43], off
	s_nop 0
	global_load_dwordx4 v[46:49], v[46:47], off
	s_nop 0
	global_load_dwordx4 v[50:53], v[50:51], off
	s_nop 0
	global_load_dwordx4 v[54:57], v[54:55], off
	s_mov_b32 s3, 0x108000
	v_add_co_u32_e32 v58, vcc, s3, v36
	s_mov_b32 s3, 0x134000
	s_nop 0
	v_addc_co_u32_e32 v59, vcc, 0, v37, vcc
	global_load_dwordx4 v[58:61], v[58:59], off
	v_add_co_u32_e32 v36, vcc, s3, v36
	s_and_b32 s3, s22, 0xffff
	s_nop 0
	v_addc_co_u32_e32 v37, vcc, 0, v37, vcc
	global_load_dwordx4 v[62:65], v[36:37], off
	s_cmpk_gt_u32 s3, 0x57
	s_cselect_b32 s3, 0xfffff500, 0
	s_cselect_b32 s22, 0x80, 0
	s_lshl_b32 s4, s21, 7
	s_add_u32 s4, s19, s4
	s_addc_u32 s5, s20, 0
	s_add_i32 s3, s3, s24
	v_lshlrev_b32_e32 v34, 1, v4
	s_and_b32 s19, s23, 0x60
	s_lshl_b32 s3, s3, 1
	v_lshl_add_u64 v[36:37], s[4:5], 0, v[34:35]
	s_or_b32 s4, s19, s22
	s_and_b32 s3, s3, 0xffffff00
	s_or_b32 s3, s4, s3
	v_or_b32_e32 v66, s3, v5
	v_ashrrev_i32_e32 v67, 31, v66
	s_waitcnt vmcnt(7)
	ds_write2_b32 v11, v26, v27 offset1:1
	ds_write2_b32 v11, v28, v29 offset0:2 offset1:3
	s_waitcnt vmcnt(6)
	ds_write2_b32 v12, v30, v31 offset1:1
	ds_write2_b32 v13, v32, v33 offset1:1
	s_waitcnt vmcnt(5)
	ds_write2_b32 v14, v42, v43 offset1:1
	ds_write2_b32 v15, v44, v45 offset1:1
	s_waitcnt vmcnt(4)
	ds_write2_b32 v16, v46, v47 offset1:1
	ds_write2_b32 v17, v48, v49 offset1:1
	s_waitcnt vmcnt(3)
	ds_write2_b32 v18, v50, v51 offset1:1
	ds_write2_b32 v19, v52, v53 offset1:1
	s_waitcnt vmcnt(2)
	ds_write2_b32 v20, v54, v55 offset1:1
	ds_write2_b32 v21, v56, v57 offset1:1
	s_waitcnt vmcnt(1)
	ds_write2_b32 v22, v58, v59 offset1:1
	ds_write2_b32 v23, v60, v61 offset1:1
	s_waitcnt vmcnt(0)
	ds_write2_b32 v24, v62, v63 offset1:1
	ds_write2_b32 v25, v64, v65 offset1:1
	s_waitcnt lgkmcnt(0)
	ds_read2_b32 v[30:31], v9 offset0:33 offset1:41
	ds_read2_b32 v[32:33], v9 offset1:8
	ds_read2_b32 v[42:43], v9 offset0:66 offset1:74
	ds_read2_b32 v[44:45], v9 offset0:99 offset1:107
	ds_read2_b32 v[46:47], v9 offset0:132 offset1:140
	ds_read2_b32 v[48:49], v9 offset0:165 offset1:173
	ds_read2_b32 v[50:51], v9 offset0:198 offset1:206
	ds_read2_b32 v[52:53], v9 offset0:231 offset1:239
	v_lshlrev_b64 v[54:55], 11, v[66:67]
	s_waitcnt lgkmcnt(6)
	v_cvt_pk_bf16_f32 v26, v32, v30
	v_lshl_add_u64 v[54:55], v[36:37], 0, v[54:55]
	v_or_b32_e32 v30, s3, v6
	s_waitcnt lgkmcnt(4)
	v_cvt_pk_bf16_f32 v27, v42, v44
	s_waitcnt lgkmcnt(2)
	v_cvt_pk_bf16_f32 v28, v46, v48
	s_waitcnt lgkmcnt(0)
	v_cvt_pk_bf16_f32 v29, v50, v52
	global_store_dwordx4 v[54:55], v[26:29], off sc1
	s_nop 1
	v_cvt_pk_bf16_f32 v26, v33, v31
	v_ashrrev_i32_e32 v31, 31, v30
	v_lshlrev_b64 v[30:31], 11, v[30:31]
	v_cvt_pk_bf16_f32 v27, v43, v45
	v_cvt_pk_bf16_f32 v28, v47, v49
	v_cvt_pk_bf16_f32 v29, v51, v53
	v_lshl_add_u64 v[30:31], v[36:37], 0, v[30:31]
	ds_read2_b32 v[32:33], v9 offset0:16 offset1:24
	ds_read2_b32 v[42:43], v9 offset0:49 offset1:57
	ds_read2_b32 v[44:45], v9 offset0:82 offset1:90
	ds_read2_b32 v[46:47], v9 offset0:115 offset1:123
	ds_read2_b32 v[48:49], v9 offset0:148 offset1:156
	ds_read2_b32 v[50:51], v9 offset0:181 offset1:189
	ds_read2_b32 v[52:53], v9 offset0:214 offset1:222
	ds_read2_b32 v[54:55], v9 offset0:247 offset1:255
	global_store_dwordx4 v[30:31], v[26:29], off sc1
	v_or_b32_e32 v30, s3, v7
	v_ashrrev_i32_e32 v31, 31, v30
	v_lshlrev_b64 v[30:31], 11, v[30:31]
	v_lshl_add_u64 v[30:31], v[36:37], 0, v[30:31]
	s_waitcnt lgkmcnt(6)
	v_cvt_pk_bf16_f32 v26, v32, v42
	s_waitcnt lgkmcnt(4)
	v_cvt_pk_bf16_f32 v27, v44, v46
	s_waitcnt lgkmcnt(2)
	v_cvt_pk_bf16_f32 v28, v48, v50
	s_waitcnt lgkmcnt(0)
	v_cvt_pk_bf16_f32 v29, v52, v54
	global_store_dwordx4 v[30:31], v[26:29], off sc1
	v_or_b32_e32 v30, s3, v8
	v_ashrrev_i32_e32 v31, 31, v30
	v_lshlrev_b64 v[30:31], 11, v[30:31]
	v_lshl_add_u64 v[30:31], v[36:37], 0, v[30:31]
	v_cvt_pk_bf16_f32 v26, v33, v43
	v_cvt_pk_bf16_f32 v27, v45, v47
	v_cvt_pk_bf16_f32 v28, v49, v51
	v_cvt_pk_bf16_f32 v29, v53, v55
	global_store_dwordx4 v[30:31], v[26:29], off sc1
	s_waitcnt lgkmcnt(0)

;     __device__ __forceinline__ const float* in(int i) const { return (const float*)(const __attribute__((address_space(1))) float*)ld(i); }
;     __device__ __forceinline__ unsigned char* ws() const { return (unsigned char*)(__attribute__((address_space(1))) unsigned char*)ld(23); }
; __device__ __forceinline__ unsigned pk2(float lo, float hi) { return cvtpk(lo, hi); }
; #define LDS_WAIT() asm volatile("s_waitcnt lgkmcnt(0)" ::: "memory")
; template <bool UPMAP>
; __device__ __forceinline__ void transpose_item(const float* W, int K, int N, bf16* WT, float* scr, int item, int lane) {
;     const int nblk = N / 32, kb = item / nblk, nb = item % nblk, k0 = 64 * kb, n0 = 32 * nb;
;     { f32x4 v[8];
; #pragma unroll
;       for (int i = 0; i < 8; ++i) v[i] = *(const f32x4*)(W + (size_t)(k0 + 8 * i + (lane >> 3)) * N + n0 + 4 * (lane & 7));
; #pragma unroll
;       for (int i = 0; i < 8; ++i) { float* d = scr + (8 * i + (lane >> 3)) * 33 + 4 * (lane & 7); d[0] = v[i][0]; d[1] = v[i][1]; d[2] = v[i][2]; d[3] = v[i][3]; } }
;     LDS_WAIT();
;     const int c = lane & 7;
; #pragma unroll
;     for (int j = 0; j < 4; ++j) { const int n = (lane >> 3) + 8 * j; const float* s = scr + (8 * c) * 33 + n;
;         v4u o; o.x = pk2(s[0 * 33], s[1 * 33]); o.y = pk2(s[2 * 33], s[3 * 33]); o.z = pk2(s[4 * 33], s[5 * 33]); o.w = pk2(s[6 * 33], s[7 * 33]);
;         const int nsrc = n0 + n; int nrow = nsrc;
;         if (UPMAP) { const int bj = nsrc / 2816, chn = nsrc - bj * 2816; nrow = (chn >> 7) * 256 + bj * 128 + (chn & 127); }
;         *(v4u*)(WT + (size_t)nrow * K + k0 + 8 * c) = o; }
;     LDS_WAIT();
; template <int PART>
; __device__ __forceinline__ void prologue(const KPD& kp, unsigned char* lds, int tid, int lane, int wave) {
;     ...
;         if (r < I_OUT) { transpose_item<false>(kp.in(I_WOUT) + (size_t)l * D * D, D, D, (bf16*)(ws + WS_WOUT) + (size_t)l * D * D, scr, r, lane); continue; } r -= I_OUT;
.LBB0_97:
	s_andn2_b64 vcc, exec, s[4:5]
	s_cbranch_vccnz .LBB0_99
	v_mov_b32_e32 v26, 0x26480
	ds_read_b64 v[26:27], v26
	s_ashr_i32 s3, s2, 31
	s_lshl_b64 s[4:5], s[2:3], 22
	v_lshlrev_b32_e32 v34, 2, v2
	s_waitcnt lgkmcnt(0)
	v_readfirstlane_b32 s20, v26
	v_readfirstlane_b32 s19, v27
	s_add_u32 s20, s20, s4
	s_addc_u32 s19, s19, s5
	s_lshl_b64 s[4:5], s[2:3], 21
	s_add_u32 s21, s11, s4
	s_addc_u32 s22, s12, s5
	s_add_i32 s3, s18, 0xfbf0
	s_bfe_u32 s23, s3, 0xb0005
	s_lshl_b32 s3, s3, 5
	s_and_b32 s3, s3, 0x3e0
	s_lshl_b32 s4, s3, 2
	s_add_u32 s4, s20, s4
	s_addc_u32 s5, s19, 0
	v_lshl_add_u64 v[26:27], s[4:5], 0, v[34:35]
	v_lshl_or_b32 v34, s23, 18, v10
	v_lshl_add_u64 v[36:37], v[26:27], 0, v[34:35]
	s_mov_b32 s4, 0x8000
	v_add_co_u32_e32 v30, vcc, s4, v36
	s_mov_b32 s4, 0x10000
	s_nop 0
	v_addc_co_u32_e32 v31, vcc, 0, v37, vcc
	v_add_co_u32_e32 v42, vcc, s4, v36
	s_mov_b32 s4, 0x18000
	s_nop 0
	v_addc_co_u32_e32 v43, vcc, 0, v37, vcc
	v_add_co_u32_e32 v46, vcc, s4, v36
	s_mov_b32 s4, 0x20000
	s_nop 0
	v_addc_co_u32_e32 v47, vcc, 0, v37, vcc
	v_add_co_u32_e32 v50, vcc, s4, v36
	s_mov_b32 s4, 0x28000
	s_nop 0
	v_addc_co_u32_e32 v51, vcc, 0, v37, vcc
	v_add_co_u32_e32 v54, vcc, s4, v36
	global_load_dwordx4 v[26:29], v[36:37], off
	s_nop 0
	global_load_dwordx4 v[30:33], v[30:31], off
	v_addc_co_u32_e32 v55, vcc, 0, v37, vcc
	global_load_dwordx4 v[42:45], v[42:43], off
	s_nop 0
	global_load_dwordx4 v[46:49], v[46:47], off
	s_nop 0
	global_load_dwordx4 v[50:53], v[50:51], off
	s_nop 0
	global_load_dwordx4 v[54:57], v[54:55], off
	s_mov_b32 s4, 0x30000
	v_add_co_u32_e32 v58, vcc, s4, v36
	s_mov_b32 s4, 0x38000
	s_nop 0
	v_addc_co_u32_e32 v59, vcc, 0, v37, vcc
	global_load_dwordx4 v[58:61], v[58:59], off
	v_add_co_u32_e32 v36, vcc, s4, v36
	s_lshl_b32 s4, s23, 7
	s_nop 0
	v_addc_co_u32_e32 v37, vcc, 0, v37, vcc
	global_load_dwordx4 v[62:65], v[36:37], off
	s_add_u32 s4, s21, s4
	v_or_b32_e32 v38, s3, v5
	s_addc_u32 s5, s22, 0
	v_lshlrev_b32_e32 v34, 1, v4
	v_lshl_add_u64 v[36:37], s[4:5], 0, v[34:35]
	v_lshlrev_b32_e32 v34, 11, v38
	v_lshl_add_u64 v[66:67], v[36:37], 0, v[34:35]
	v_or_b32_e32 v39, s3, v6
	v_lshlrev_b32_e32 v34, 11, v39
	v_lshl_add_u64 v[68:69], v[36:37], 0, v[34:35]
	s_waitcnt vmcnt(7)
	ds_write2_b32 v11, v26, v27 offset1:1
	ds_write2_b32 v11, v28, v29 offset0:2 offset1:3
	s_waitcnt vmcnt(6)
	ds_write2_b32 v12, v30, v31 offset1:1
	ds_write2_b32 v13, v32, v33 offset1:1
	s_waitcnt vmcnt(5)
	ds_write2_b32 v14, v42, v43 offset1:1
	ds_write2_b32 v15, v44, v45 offset1:1
	s_waitcnt vmcnt(4)
	ds_write2_b32 v16, v46, v47 offset1:1
	ds_write2_b32 v17, v48, v49 offset1:1
	s_waitcnt vmcnt(3)
	ds_write2_b32 v18, v50, v51 offset1:1
	ds_write2_b32 v19, v52, v53 offset1:1
	s_waitcnt vmcnt(2)
	ds_write2_b32 v20, v54, v55 offset1:1
	ds_write2_b32 v21, v56, v57 offset1:1
	s_waitcnt vmcnt(1)
	ds_write2_b32 v22, v58, v59 offset1:1
	ds_write2_b32 v23, v60, v61 offset1:1
	s_waitcnt vmcnt(0)
	ds_write2_b32 v24, v62, v63 offset1:1
	ds_write2_b32 v25, v64, v65 offset1:1
	s_waitcnt lgkmcnt(0)
	ds_read2_b32 v[30:31], v9 offset0:33 offset1:41
	ds_read2_b32 v[32:33], v9 offset1:8
	ds_read2_b32 v[42:43], v9 offset0:66 offset1:74
	ds_read2_b32 v[44:45], v9 offset0:99 offset1:107
	ds_read2_b32 v[46:47], v9 offset0:132 offset1:140
	ds_read2_b32 v[48:49], v9 offset0:165 offset1:173
	ds_read2_b32 v[50:51], v9 offset0:198 offset1:206
	ds_read2_b32 v[52:53], v9 offset0:231 offset1:239
	ds_read2_b32 v[54:55], v9 offset0:16 offset1:24
	ds_read2_b32 v[56:57], v9 offset0:49 offset1:57
	ds_read2_b32 v[58:59], v9 offset0:82 offset1:90
	ds_read2_b32 v[60:61], v9 offset0:115 offset1:123
	ds_read2_b32 v[62:63], v9 offset0:148 offset1:156
	s_waitcnt lgkmcnt(11)
	v_cvt_pk_bf16_f32 v26, v32, v30
	s_waitcnt lgkmcnt(9)
	v_cvt_pk_bf16_f32 v27, v42, v44
	s_waitcnt lgkmcnt(7)
	v_cvt_pk_bf16_f32 v28, v46, v48
	s_waitcnt lgkmcnt(5)
	v_cvt_pk_bf16_f32 v29, v50, v52
	global_store_dwordx4 v[66:67], v[26:29], off sc1
	v_cvt_pk_bf16_f32 v30, v33, v31
	v_cvt_pk_bf16_f32 v31, v43, v45
	v_cvt_pk_bf16_f32 v32, v47, v49
	ds_read2_b32 v[42:43], v9 offset0:181 offset1:189
	ds_read2_b32 v[44:45], v9 offset0:214 offset1:222
	ds_read2_b32 v[46:47], v9 offset0:247 offset1:255
	v_cvt_pk_bf16_f32 v33, v51, v53
	global_store_dwordx4 v[68:69], v[30:33], off sc1
	s_waitcnt lgkmcnt(6)
	v_cvt_pk_bf16_f32 v26, v54, v56
	s_waitcnt lgkmcnt(4)
	v_cvt_pk_bf16_f32 v27, v58, v60
	s_waitcnt lgkmcnt(2)
	v_cvt_pk_bf16_f32 v28, v62, v42
	s_waitcnt lgkmcnt(0)
	v_cvt_pk_bf16_f32 v29, v44, v46
	v_or_b32_e32 v30, s3, v7
	v_lshlrev_b32_e32 v34, 11, v30
	v_lshl_add_u64 v[30:31], v[36:37], 0, v[34:35]
	global_store_dwordx4 v[30:31], v[26:29], off sc1
	v_or_b32_e32 v30, s3, v8
	v_lshlrev_b32_e32 v34, 11, v30
	v_lshl_add_u64 v[30:31], v[36:37], 0, v[34:35]
	v_cvt_pk_bf16_f32 v26, v55, v57
	v_cvt_pk_bf16_f32 v27, v59, v61
	v_cvt_pk_bf16_f32 v28, v63, v43
	v_cvt_pk_bf16_f32 v29, v45, v47
	global_store_dwordx4 v[30:31], v[26:29], off sc1
	s_waitcnt lgkmcnt(0)

;     __device__ __forceinline__ const float* in(int i) const { return (const float*)(const __attribute__((address_space(1))) float*)ld(i); }
;     __device__ __forceinline__ unsigned char* ws() const { return (unsigned char*)(__attribute__((address_space(1))) unsigned char*)ld(23); }
; __device__ __forceinline__ unsigned pk2(float lo, float hi) { return cvtpk(lo, hi); }
; #define LDS_WAIT() asm volatile("s_waitcnt lgkmcnt(0)" ::: "memory")
; template <bool UPMAP>
; __device__ __forceinline__ void transpose_item(const float* W, int K, int N, bf16* WT, float* scr, int item, int lane) {
;     const int nblk = N / 32, kb = item / nblk, nb = item % nblk, k0 = 64 * kb, n0 = 32 * nb;
;     { f32x4 v[8];
; #pragma unroll
;       for (int i = 0; i < 8; ++i) v[i] = *(const f32x4*)(W + (size_t)(k0 + 8 * i + (lane >> 3)) * N + n0 + 4 * (lane & 7));
; #pragma unroll
;       for (int i = 0; i < 8; ++i) { float* d = scr + (8 * i + (lane >> 3)) * 33 + 4 * (lane & 7); d[0] = v[i][0]; d[1] = v[i][1]; d[2] = v[i][2]; d[3] = v[i][3]; } }
;     LDS_WAIT();
;     const int c = lane & 7;
; #pragma unroll
;     for (int j = 0; j < 4; ++j) { const int n = (lane >> 3) + 8 * j; const float* s = scr + (8 * c) * 33 + n;
;         v4u o; o.x = pk2(s[0 * 33], s[1 * 33]); o.y = pk2(s[2 * 33], s[3 * 33]); o.z = pk2(s[4 * 33], s[5 * 33]); o.w = pk2(s[6 * 33], s[7 * 33]);
;         const int nsrc = n0 + n; int nrow = nsrc;
;         if (UPMAP) { const int bj = nsrc / 2816, chn = nsrc - bj * 2816; nrow = (chn >> 7) * 256 + bj * 128 + (chn & 127); }
;         *(v4u*)(WT + (size_t)nrow * K + k0 + 8 * c) = o; }
;     LDS_WAIT();
; }
; template <int PART>
; __device__ __forceinline__ void prologue(const KPD& kp, unsigned char* lds, int tid, int lane, int wave) {
;     ...
;         if (r < I_IN) { transpose_item<false>(kp.in(I_WIN) + (size_t)l * D * INW, D, INW, (bf16*)(ws + WS_WIN) + (size_t)l * INP * D, scr, r, lane); continue; } r -= I_IN;
.LBB0_101:
	v_mov_b32_e32 v26, 0x26438
	ds_read_b64 v[26:27], v26
	s_mul_i32 s4, s2, 0x820000
	s_mul_hi_i32 s3, s2, 0x820000
	s_mul_hi_i32 s5, s2, 0x480000
	s_mul_i32 s2, s2, 0x480000
	s_waitcnt lgkmcnt(0)
	v_readfirstlane_b32 s20, v26
	v_readfirstlane_b32 s19, v27
	s_add_u32 s20, s20, s4
	s_addc_u32 s21, s19, s3
	s_add_u32 s22, s13, s2
	s_mul_i32 s2, s18, 0xfc1
	s_addc_u32 s23, s16, s5
	s_lshr_b32 s3, s2, 31
	s_ashr_i32 s2, s2, 18
	s_add_i32 s2, s2, s3
	s_mul_i32 s3, s2, 0x41
	s_sub_i32 s3, s18, s3
	s_sext_i32_i16 s3, s3
	s_lshl_b32 s4, s2, 6
	s_lshl_b32 s2, s3, 5
	s_ashr_i32 s3, s2, 31
	s_lshl_b64 s[18:19], s[2:3], 2
	v_or_b32_e32 v28, s4, v5
	s_add_u32 s18, s20, s18
	s_addc_u32 s19, s21, s19
	v_lshlrev_b32_e32 v34, 2, v2
	v_mul_i32_i24_e32 v28, 0x820, v28
	v_lshl_add_u64 v[26:27], s[18:19], 0, v[34:35]
	v_ashrrev_i32_e32 v29, 31, v28
	v_lshl_add_u64 v[36:37], v[28:29], 2, v[26:27]
	s_mov_b32 s3, 0x10000
	v_add_co_u32_e32 v30, vcc, s3, v36
	s_mov_b32 s3, 0x20000
	s_nop 0
	v_addc_co_u32_e32 v31, vcc, 0, v37, vcc
	v_add_co_u32_e32 v42, vcc, s3, v36
	s_mov_b32 s3, 0x30000
	s_nop 0
	v_addc_co_u32_e32 v43, vcc, 0, v37, vcc
	v_add_co_u32_e32 v46, vcc, s3, v36
	s_mov_b32 s3, 0x41000
	s_nop 0
	v_addc_co_u32_e32 v47, vcc, 0, v37, vcc
	v_add_co_u32_e32 v50, vcc, s3, v36
	s_mov_b32 s3, 0x51000
	s_nop 0
	v_addc_co_u32_e32 v51, vcc, 0, v37, vcc
	v_add_co_u32_e32 v54, vcc, s3, v36
	global_load_dwordx4 v[26:29], v[36:37], off
	s_nop 0
	global_load_dwordx4 v[30:33], v[30:31], off offset:1024
	v_addc_co_u32_e32 v55, vcc, 0, v37, vcc
	global_load_dwordx4 v[42:45], v[42:43], off offset:2048
	s_nop 0
	global_load_dwordx4 v[46:49], v[46:47], off offset:3072
	s_nop 0
	global_load_dwordx4 v[50:53], v[50:51], off
	s_nop 0
	global_load_dwordx4 v[54:57], v[54:55], off offset:1024
	s_mov_b32 s3, 0x61000
	v_add_co_u32_e32 v58, vcc, s3, v36
	s_mov_b32 s3, 0x71000
	s_nop 0
	v_addc_co_u32_e32 v59, vcc, 0, v37, vcc
	global_load_dwordx4 v[58:61], v[58:59], off offset:2048
	v_add_co_u32_e32 v36, vcc, s3, v36
	s_ashr_i32 s5, s4, 31
	s_nop 0
	v_addc_co_u32_e32 v37, vcc, 0, v37, vcc
	global_load_dwordx4 v[62:65], v[36:37], off offset:3072
	s_lshl_b64 s[4:5], s[4:5], 1
	v_or_b32_e32 v36, s2, v5
	s_add_u32 s4, s22, s4
	v_ashrrev_i32_e32 v37, 31, v36
	v_lshlrev_b32_e32 v34, 1, v4
	s_addc_u32 s5, s23, s5
	v_or_b32_e32 v66, s2, v6
	v_lshlrev_b64 v[36:37], 11, v[36:37]
	v_lshl_add_u64 v[68:69], s[4:5], 0, v[34:35]
	v_lshl_add_u64 v[36:37], v[68:69], 0, v[36:37]
	v_ashrrev_i32_e32 v67, 31, v66
	s_waitcnt vmcnt(7)
	ds_write2_b32 v11, v26, v27 offset1:1
	ds_write2_b32 v11, v28, v29 offset0:2 offset1:3
	s_waitcnt vmcnt(6)
	ds_write2_b32 v12, v30, v31 offset1:1
	ds_write2_b32 v13, v32, v33 offset1:1
	s_waitcnt vmcnt(5)
	ds_write2_b32 v14, v42, v43 offset1:1
	ds_write2_b32 v15, v44, v45 offset1:1
	s_waitcnt vmcnt(4)
	ds_write2_b32 v16, v46, v47 offset1:1
	ds_write2_b32 v17, v48, v49 offset1:1
	s_waitcnt vmcnt(3)
	ds_write2_b32 v18, v50, v51 offset1:1
	ds_write2_b32 v19, v52, v53 offset1:1
	s_waitcnt vmcnt(2)
	ds_write2_b32 v20, v54, v55 offset1:1
	ds_write2_b32 v21, v56, v57 offset1:1
	s_waitcnt vmcnt(1)
	ds_write2_b32 v22, v58, v59 offset1:1
	ds_write2_b32 v23, v60, v61 offset1:1
	s_waitcnt vmcnt(0)
	ds_write2_b32 v24, v62, v63 offset1:1
	ds_write2_b32 v25, v64, v65 offset1:1
	s_waitcnt lgkmcnt(0)
	ds_read2_b32 v[30:31], v9 offset0:33 offset1:41
	ds_read2_b32 v[32:33], v9 offset1:8
	ds_read2_b32 v[42:43], v9 offset0:66 offset1:74
	ds_read2_b32 v[44:45], v9 offset0:99 offset1:107
	ds_read2_b32 v[46:47], v9 offset0:132 offset1:140
	ds_read2_b32 v[48:49], v9 offset0:165 offset1:173
	ds_read2_b32 v[50:51], v9 offset0:198 offset1:206
	ds_read2_b32 v[52:53], v9 offset0:231 offset1:239
	s_waitcnt lgkmcnt(6)
	v_cvt_pk_bf16_f32 v26, v32, v30
	s_waitcnt lgkmcnt(4)
	v_cvt_pk_bf16_f32 v27, v42, v44
	s_waitcnt lgkmcnt(2)
	v_cvt_pk_bf16_f32 v28, v46, v48
	s_waitcnt lgkmcnt(0)
	v_cvt_pk_bf16_f32 v29, v50, v52
	global_store_dwordx4 v[36:37], v[26:29], off sc1
	v_cvt_pk_bf16_f32 v30, v33, v31
	v_cvt_pk_bf16_f32 v31, v43, v45
	v_cvt_pk_bf16_f32 v32, v47, v49
	v_cvt_pk_bf16_f32 v33, v51, v53
	ds_read2_b32 v[36:37], v9 offset0:16 offset1:24
	ds_read2_b32 v[42:43], v9 offset0:49 offset1:57
	ds_read2_b32 v[44:45], v9 offset0:82 offset1:90
	ds_read2_b32 v[46:47], v9 offset0:115 offset1:123
	ds_read2_b32 v[48:49], v9 offset0:148 offset1:156
	ds_read2_b32 v[50:51], v9 offset0:181 offset1:189
	ds_read2_b32 v[52:53], v9 offset0:214 offset1:222
	ds_read2_b32 v[54:55], v9 offset0:247 offset1:255
	v_lshlrev_b64 v[26:27], 11, v[66:67]
	v_lshl_add_u64 v[26:27], v[68:69], 0, v[26:27]
	global_store_dwordx4 v[26:27], v[30:33], off sc1
	s_waitcnt lgkmcnt(6)
	v_cvt_pk_bf16_f32 v26, v36, v42
	s_waitcnt lgkmcnt(4)
	v_cvt_pk_bf16_f32 v27, v44, v46
	s_waitcnt lgkmcnt(2)
	v_cvt_pk_bf16_f32 v28, v48, v50
	s_waitcnt lgkmcnt(0)
	v_cvt_pk_bf16_f32 v29, v52, v54
	v_or_b32_e32 v30, s2, v7
	v_ashrrev_i32_e32 v31, 31, v30
	v_lshlrev_b64 v[30:31], 11, v[30:31]
	v_lshl_add_u64 v[30:31], v[68:69], 0, v[30:31]
	global_store_dwordx4 v[30:31], v[26:29], off sc1
	v_or_b32_e32 v30, s2, v8
	v_ashrrev_i32_e32 v31, 31, v30
	v_lshlrev_b64 v[30:31], 11, v[30:31]
	v_lshl_add_u64 v[30:31], v[68:69], 0, v[30:31]
	v_cvt_pk_bf16_f32 v26, v37, v43
	v_cvt_pk_bf16_f32 v27, v45, v47
	v_cvt_pk_bf16_f32 v28, v49, v51
	v_cvt_pk_bf16_f32 v29, v53, v55
	global_store_dwordx4 v[30:31], v[26:29], off sc1
	s_waitcnt lgkmcnt(0)
	s_branch .LBB0_89

;     __device__ __forceinline__ unsigned char* ws() const { return (unsigned char*)(__attribute__((address_space(1))) unsigned char*)ld(23); }
; template <int PART>
; __device__ __forceinline__ void prologue(const KPD& kp, unsigned char* lds, int tid, int lane, int wave) {
;     ...
;     { const int gt = blockIdx.x * 512 + tid, NT = gridDim.x * 512; constexpr int PADV = (INP - INW) * D * 2 / 16;
;       for (int i = gt; i < 2 * PADV; i += NT) { const int l = i / PADV, r = i % PADV; *((v4u*)((bf16*)(ws + WS_WIN) + (size_t)l * INP * D + (size_t)INW * D) + r) = (v4u){0u, 0u, 0u, 0u}; } }
.LBB0_106:
	s_mov_b32 s6, 0x92492493
	v_mul_hi_i32 v3, v2, s6
	v_add_u32_e32 v3, v3, v2
	v_lshrrev_b32_e32 v4, 31, v3
	v_ashrrev_i32_e32 v3, 14, v3
	v_add_u32_e32 v3, v3, v4
	v_mul_i32_i24_e32 v5, 0x7000, v3
	v_mul_i32_i24_e32 v4, 0x900, v3
	v_sub_u32_e32 v6, v2, v5
	v_ashrrev_i32_e32 v5, 31, v4
	v_lshlrev_b64 v[4:5], 11, v[4:5]
	v_add_u32_e32 v2, s80, v2
	v_ashrrev_i32_e32 v7, 31, v6
	s_mov_b32 s6, 0xdfff
	v_lshl_add_u64 v[4:5], s[0:1], 0, v[4:5]
	v_cmp_lt_i32_e32 vcc, s6, v2
	v_lshl_add_u64 v[4:5], v[6:7], 4, v[4:5]
	s_or_b64 s[4:5], vcc, s[4:5]
	v_add_co_u32_e32 v4, vcc, 0x610000, v4
	s_nop 1
	v_addc_co_u32_e32 v5, vcc, 0, v5, vcc
	global_store_dwordx4 v[4:5], v[70:73], off sc1
	s_andn2_b64 exec, exec, s[4:5]
	s_cbranch_execnz .LBB0_106

; template <int NR>
; __device__ __forceinline__ void norm_group(int m0, const float* src_lat, const float* src_ctx, bf16* H, const float* gain, const float* mod, int shoff, int scoff, int lane, const float* part, float* ctx_out) {
;     const float* xr = (m0 < MLAT) ? src_lat + (size_t)m0 * D : src_ctx + (size_t)(m0 - MLAT) * D;
;     const int b = (m0 < MLAT) ? (m0 >> 13) : 4;
;     f32x4 v[NR][4]; float rstd[NR];
; #pragma unroll
;     for (int i = 0; i < NR; ++i)
; #pragma unroll
;         for (int j = 0; j < 4; ++j) v[i][j] = *((const f32x4*)(xr + (size_t)i * D) + lane + 64 * j);
;     if (part && m0 >= MLAT) {
; #pragma unroll
;         for (int i = 0; i < NR; ++i)
; #pragma unroll
;             for (int j = 0; j < 4; ++j) { const size_t o = (size_t)(m0 - MLAT + i) * D + 4 * (lane + 64 * j);
;                 const f32x4 p0 = *(const f32x4*)(part + o), p1 = *(const f32x4*)(part + (size_t)MCTX * D + o), p2 = *(const f32x4*)(part + (size_t)2 * MCTX * D + o), p3 = *(const f32x4*)(part + (size_t)3 * MCTX * D + o);
;                 v[i][j] = v[i][j] + ((p0 + p1) + (p2 + p3)); *(f32x4*)(ctx_out + o) = v[i][j]; }
;     }
; #pragma unroll
;     for (int i = 0; i < NR; ++i) { float s = 0.f;
; #pragma unroll
;         for (int j = 0; j < 4; ++j) s += (v[i][j].x * v[i][j].x + v[i][j].y * v[i][j].y) + (v[i][j].z * v[i][j].z + v[i][j].w * v[i][j].w);
;         rstd[i] = 1.0f / sqrtf(wave_sum(s) * (1.f / D) + EPS); }
.LBB0_110:
	s_ashr_i32 s9, s8, 31
	s_lshl_b64 s[0:1], s[8:9], 12
	v_lshl_add_u64 v[6:7], v[36:37], 0, s[0:1]
	global_load_dwordx4 v[70:73], v[6:7], off
	global_load_dwordx4 v[54:57], v[6:7], off offset:1024
	global_load_dwordx4 v[30:33], v[6:7], off offset:2048
	global_load_dwordx4 v[14:17], v[6:7], off offset:3072
	v_add_co_u32_e32 v2, vcc, 0x1000, v6
	s_waitcnt vmcnt(3)
	v_pk_mul_f32 v[96:97], v[72:73], v[72:73]
	v_addc_co_u32_e32 v3, vcc, 0, v7, vcc
	global_load_dwordx4 v[66:69], v[2:3], off
	global_load_dwordx4 v[46:49], v[2:3], off offset:1024
	global_load_dwordx4 v[18:21], v[2:3], off offset:2048
	s_nop 0
	global_load_dwordx4 v[2:5], v[2:3], off offset:3072
	v_pk_mul_f32 v[98:99], v[70:71], v[70:71]
	s_waitcnt vmcnt(4)
	v_mul_f32_e32 v38, v14, v14
	v_pk_mov_b32 v[100:101], v[98:99], v[96:97] op_sel:[1,0]
	v_mov_b32_e32 v99, v97
	v_pk_add_f32 v[96:97], v[100:101], v[98:99]
	v_pk_mul_f32 v[98:99], v[56:57], v[56:57]
	v_pk_mul_f32 v[100:101], v[54:55], v[54:55]
	v_mul_f32_e32 v39, v15, v15
	v_pk_mov_b32 v[102:103], v[100:101], v[98:99] op_sel:[1,0]
	v_mov_b32_e32 v101, v99
	v_pk_add_f32 v[98:99], v[102:103], v[100:101]
	v_pk_add_f32 v[96:97], v[96:97], v[96:97] op_sel:[0,1] op_sel_hi:[1,0]
	v_pk_add_f32 v[98:99], v[98:99], v[98:99] op_sel:[0,1] op_sel_hi:[1,0]
	v_mov_b32_e32 v97, v38
	v_mov_b32_e32 v99, v39
	v_mul_f32_e32 v80, v31, v31
	v_pk_add_f32 v[96:97], v[96:97], v[98:99]
	v_pk_fma_f32 v[98:99], v[30:31], v[30:31], v[80:81] op_sel_hi:[1,1,0]
	v_mul_f32_e32 v80, v33, v33
	v_mul_f32_e32 v40, v16, v16
	v_mul_f32_e32 v41, v17, v17
	v_pk_fma_f32 v[100:101], v[32:33], v[32:33], v[80:81] op_sel_hi:[1,1,0]
	v_mov_b32_e32 v99, v40
	v_mov_b32_e32 v101, v41
	v_pk_add_f32 v[98:99], v[98:99], v[100:101]
	v_add_co_u32_e32 v8, vcc, s96, v6
	v_pk_add_f32 v[96:97], v[96:97], v[98:99]
	s_nop 0
	v_addc_co_u32_e32 v9, vcc, 0, v7, vcc
	v_add_f32_e32 v38, v96, v97
	ds_bpermute_b32 v39, v89, v38
	v_add_co_u32_e32 v6, vcc, s87, v6
	s_waitcnt lgkmcnt(0)
	v_add_f32_e32 v38, v38, v39
	ds_bpermute_b32 v39, v90, v38
	v_addc_co_u32_e32 v7, vcc, 0, v7, vcc
	global_load_dwordx4 v[62:65], v[6:7], off offset:-4096
	global_load_dwordx4 v[50:53], v[8:9], off offset:1024
	global_load_dwordx4 v[26:29], v[8:9], off offset:2048
	global_load_dwordx4 v[10:13], v[8:9], off offset:3072
	global_load_dwordx4 v[58:61], v[6:7], off
	global_load_dwordx4 v[42:45], v[6:7], off offset:1024
	global_load_dwordx4 v[22:25], v[6:7], off offset:2048
	s_nop 0
	global_load_dwordx4 v[6:9], v[6:7], off offset:3072
	s_waitcnt lgkmcnt(0)
	v_add_f32_e32 v38, v38, v39
	ds_bpermute_b32 v39, v91, v38
	s_waitcnt lgkmcnt(0)
	v_add_f32_e32 v38, v38, v39
	ds_bpermute_b32 v39, v92, v38
	s_waitcnt lgkmcnt(0)
	v_add_f32_e32 v38, v38, v39
	ds_bpermute_b32 v39, v93, v38
	s_waitcnt lgkmcnt(0)
	v_add_f32_e32 v38, v38, v39
	ds_bpermute_b32 v39, v94, v38
	s_waitcnt lgkmcnt(0)
	v_add_f32_e32 v38, v38, v39
	v_fmamk_f32 v38, v38, 0x3a800000, v205
	v_cmp_gt_f32_e32 vcc, s88, v38
	v_mul_f32_e32 v39, 0x4f800000, v38
	s_waitcnt vmcnt(11)
	v_pk_mul_f32 v[96:97], v[68:69], v[68:69]
	v_cndmask_b32_e32 v38, v38, v39, vcc
	v_sqrt_f32_e32 v39, v38
	v_pk_mul_f32 v[98:99], v[66:67], v[66:67]
	s_waitcnt vmcnt(9)
	v_mul_f32_e32 v82, v19, v19
	v_pk_mov_b32 v[100:101], v[98:99], v[96:97] op_sel:[1,0]
	v_add_u32_e32 v40, -1, v39
	v_fma_f32 v41, -v40, v39, v38
	v_cmp_ge_f32_e64 s[0:1], 0, v41
	v_add_u32_e32 v41, 1, v39
	v_mov_b32_e32 v99, v97
	v_cndmask_b32_e64 v40, v39, v40, s[0:1]
	v_fma_f32 v39, -v41, v39, v38
	v_cmp_lt_f32_e64 s[0:1], 0, v39
	v_pk_add_f32 v[96:97], v[100:101], v[98:99]
	v_pk_mul_f32 v[98:99], v[48:49], v[48:49]
	v_cndmask_b32_e64 v39, v40, v41, s[0:1]
	v_mul_f32_e32 v40, 0x37800000, v39
	v_cndmask_b32_e32 v39, v39, v40, vcc
	v_cmp_class_f32_e32 vcc, v38, v206
	v_pk_mul_f32 v[100:101], v[46:47], v[46:47]
	v_pk_add_f32 v[96:97], v[96:97], v[96:97] op_sel:[0,1] op_sel_hi:[1,0]
	v_cndmask_b32_e32 v38, v39, v38, vcc
	v_div_scale_f32 v39, s[0:1], v38, v38, 1.0
	v_rcp_f32_e32 v40, v39
	v_pk_mov_b32 v[102:103], v[100:101], v[98:99] op_sel:[1,0]
	v_mov_b32_e32 v101, v99
	v_pk_add_f32 v[98:99], v[102:103], v[100:101]
	v_fma_f32 v41, -v39, v40, 1.0
	v_fmac_f32_e32 v40, v41, v40
	v_div_scale_f32 v41, vcc, 1.0, v38, 1.0
	v_mul_f32_e32 v77, v41, v40
	v_fma_f32 v80, -v39, v77, v41
	v_fmac_f32_e32 v77, v80, v40
	v_fma_f32 v39, -v39, v77, v41
	v_div_fmas_f32 v39, v39, v40, v77
	v_div_fixup_f32 v80, v39, v38, 1.0
	s_waitcnt vmcnt(8)
	v_mul_f32_e32 v38, v2, v2
	v_mul_f32_e32 v39, v3, v3
	v_pk_add_f32 v[98:99], v[98:99], v[98:99] op_sel:[0,1] op_sel_hi:[1,0]
	v_mov_b32_e32 v97, v38
	v_mov_b32_e32 v99, v39
	v_pk_add_f32 v[96:97], v[96:97], v[98:99]
	v_pk_fma_f32 v[98:99], v[18:19], v[18:19], v[82:83] op_sel_hi:[1,1,0]
	v_mul_f32_e32 v82, v21, v21
	v_mul_f32_e32 v40, v4, v4
	v_mul_f32_e32 v41, v5, v5
	v_pk_fma_f32 v[100:101], v[20:21], v[20:21], v[82:83] op_sel_hi:[1,1,0]
	v_mov_b32_e32 v99, v40
	v_mov_b32_e32 v101, v41
	v_pk_add_f32 v[98:99], v[98:99], v[100:101]
	s_waitcnt vmcnt(5)
	v_mul_f32_e32 v84, v27, v27
	v_pk_add_f32 v[96:97], v[96:97], v[98:99]
	v_pk_mul_f32 v[98:99], v[62:63], v[62:63]
	v_add_f32_e32 v38, v96, v97
	ds_bpermute_b32 v39, v89, v38
	v_pk_mul_f32 v[96:97], v[64:65], v[64:65]
	s_waitcnt vmcnt(1)
	v_mul_f32_e32 v86, v23, v23
	v_pk_mov_b32 v[100:101], v[98:99], v[96:97] op_sel:[1,0]
	v_mov_b32_e32 v99, v97
	s_waitcnt lgkmcnt(0)
	v_add_f32_e32 v38, v38, v39
	ds_bpermute_b32 v39, v90, v38
	v_pk_add_f32 v[96:97], v[100:101], v[98:99]
	v_pk_mul_f32 v[98:99], v[52:53], v[52:53]
	v_pk_mul_f32 v[100:101], v[50:51], v[50:51]
	v_pk_add_f32 v[96:97], v[96:97], v[96:97] op_sel:[0,1] op_sel_hi:[1,0]
	s_waitcnt lgkmcnt(0)
; template <int NR>
; __device__ __forceinline__ void norm_group(int m0, const float* src_lat, const float* src_ctx, bf16* H, const float* gain, const float* mod, int shoff, int scoff, int lane, const float* part, float* ctx_out) {
;     ...
;     for (int i = 0; i < NR; ++i) { float s = 0.f;
; #pragma unroll
;         for (int j = 0; j < 4; ++j) s += (v[i][j].x * v[i][j].x + v[i][j].y * v[i][j].y) + (v[i][j].z * v[i][j].z + v[i][j].w * v[i][j].w);
;         rstd[i] = 1.0f / sqrtf(wave_sum(s) * (1.f / D) + EPS); }
;     ...
;         for (int i = 0; i < NR; ++i) { const f32x4 y = v[i][j] * rstd[i] * gs + sh;
	v_add_f32_e32 v38, v38, v39
	ds_bpermute_b32 v39, v91, v38
	v_pk_mov_b32 v[102:103], v[100:101], v[98:99] op_sel:[1,0]
	v_mov_b32_e32 v101, v99
	v_pk_add_f32 v[98:99], v[102:103], v[100:101]
	v_pk_mul_f32 v[70:71], v[70:71], v[80:81] op_sel_hi:[1,0]
	s_waitcnt lgkmcnt(0)
	v_add_f32_e32 v38, v38, v39
	ds_bpermute_b32 v39, v92, v38
	v_pk_add_f32 v[98:99], v[98:99], v[98:99] op_sel:[0,1] op_sel_hi:[1,0]
	v_pk_mul_f32 v[72:73], v[72:73], v[80:81] op_sel_hi:[1,0]
	v_pk_mul_f32 v[54:55], v[54:55], v[80:81] op_sel_hi:[1,0]
	v_pk_mul_f32 v[56:57], v[56:57], v[80:81] op_sel_hi:[1,0]
	s_waitcnt lgkmcnt(0)
	v_add_f32_e32 v38, v38, v39
	ds_bpermute_b32 v39, v93, v38
	v_pk_mul_f32 v[30:31], v[30:31], v[80:81] op_sel_hi:[1,0]
	v_pk_mul_f32 v[32:33], v[32:33], v[80:81] op_sel_hi:[1,0]
	v_pk_mul_f32 v[14:15], v[14:15], v[80:81] op_sel_hi:[1,0]
	v_pk_mul_f32 v[16:17], v[16:17], v[80:81] op_sel_hi:[1,0]
	s_waitcnt lgkmcnt(0)
	v_add_f32_e32 v38, v38, v39
	ds_bpermute_b32 v39, v94, v38
	s_waitcnt lgkmcnt(0)
	v_add_f32_e32 v38, v38, v39
	v_fmamk_f32 v38, v38, 0x3a800000, v205
	v_cmp_gt_f32_e32 vcc, s88, v38
	v_mul_f32_e32 v39, 0x4f800000, v38
	s_nop 0
	v_cndmask_b32_e32 v38, v38, v39, vcc
	v_sqrt_f32_e32 v39, v38
	s_nop 0
	v_add_u32_e32 v40, -1, v39
	v_fma_f32 v41, -v40, v39, v38
	v_cmp_ge_f32_e64 s[0:1], 0, v41
	v_add_u32_e32 v41, 1, v39
	s_nop 0
	v_cndmask_b32_e64 v40, v39, v40, s[0:1]
	v_fma_f32 v39, -v41, v39, v38
	v_cmp_lt_f32_e64 s[0:1], 0, v39
	s_nop 1
	v_cndmask_b32_e64 v39, v40, v41, s[0:1]
	v_mul_f32_e32 v40, 0x37800000, v39
	v_cndmask_b32_e32 v39, v39, v40, vcc
	v_cmp_class_f32_e32 vcc, v38, v206
	s_nop 1
	v_cndmask_b32_e32 v38, v39, v38, vcc
	v_div_scale_f32 v39, s[0:1], v38, v38, 1.0
	v_rcp_f32_e32 v40, v39
	s_nop 0
	v_fma_f32 v41, -v39, v40, 1.0
	v_fmac_f32_e32 v40, v41, v40
	v_div_scale_f32 v41, vcc, 1.0, v38, 1.0
	v_mul_f32_e32 v77, v41, v40
	v_fma_f32 v82, -v39, v77, v41
	v_fmac_f32_e32 v77, v82, v40
	v_fma_f32 v39, -v39, v77, v41
	v_div_fmas_f32 v39, v39, v40, v77
	v_div_fixup_f32 v82, v39, v38, 1.0
	v_mul_f32_e32 v38, v10, v10
	v_mul_f32_e32 v39, v11, v11
	v_mov_b32_e32 v97, v38
	v_mov_b32_e32 v99, v39
	v_pk_add_f32 v[96:97], v[96:97], v[98:99]
	v_pk_fma_f32 v[98:99], v[26:27], v[26:27], v[84:85] op_sel_hi:[1,1,0]
	v_mul_f32_e32 v84, v29, v29
	v_mul_f32_e32 v40, v12, v12
	v_mul_f32_e32 v41, v13, v13
	v_pk_fma_f32 v[100:101], v[28:29], v[28:29], v[84:85] op_sel_hi:[1,1,0]
	v_mov_b32_e32 v99, v40
	v_mov_b32_e32 v101, v41
	v_pk_add_f32 v[98:99], v[98:99], v[100:101]
	v_pk_mul_f32 v[66:67], v[66:67], v[82:83] op_sel_hi:[1,0]
	v_pk_add_f32 v[96:97], v[96:97], v[98:99]
	v_pk_mul_f32 v[98:99], v[58:59], v[58:59]
	v_add_f32_e32 v38, v96, v97
	ds_bpermute_b32 v39, v89, v38
	v_pk_mul_f32 v[96:97], v[60:61], v[60:61]
	v_pk_mul_f32 v[68:69], v[68:69], v[82:83] op_sel_hi:[1,0]
	v_pk_mov_b32 v[100:101], v[98:99], v[96:97] op_sel:[1,0]
	v_mov_b32_e32 v99, v97
	s_waitcnt lgkmcnt(0)
	v_add_f32_e32 v38, v38, v39
	ds_bpermute_b32 v39, v90, v38
	v_pk_add_f32 v[96:97], v[100:101], v[98:99]
	v_pk_mul_f32 v[98:99], v[44:45], v[44:45]
	v_pk_mul_f32 v[100:101], v[42:43], v[42:43]
	v_pk_add_f32 v[96:97], v[96:97], v[96:97] op_sel:[0,1] op_sel_hi:[1,0]
	s_waitcnt lgkmcnt(0)
	v_add_f32_e32 v38, v38, v39
	ds_bpermute_b32 v39, v91, v38
	v_pk_mov_b32 v[102:103], v[100:101], v[98:99] op_sel:[1,0]
	v_mov_b32_e32 v101, v99
	v_pk_add_f32 v[98:99], v[102:103], v[100:101]
	v_pk_mul_f32 v[46:47], v[46:47], v[82:83] op_sel_hi:[1,0]
	s_waitcnt lgkmcnt(0)
	v_add_f32_e32 v38, v38, v39
	ds_bpermute_b32 v39, v92, v38
	v_pk_add_f32 v[98:99], v[98:99], v[98:99] op_sel:[0,1] op_sel_hi:[1,0]
	v_pk_mul_f32 v[48:49], v[48:49], v[82:83] op_sel_hi:[1,0]
	v_pk_mul_f32 v[18:19], v[18:19], v[82:83] op_sel_hi:[1,0]
	v_pk_mul_f32 v[20:21], v[20:21], v[82:83] op_sel_hi:[1,0]
	s_waitcnt lgkmcnt(0)
	v_add_f32_e32 v38, v38, v39
	ds_bpermute_b32 v39, v93, v38
	v_pk_mul_f32 v[2:3], v[2:3], v[82:83] op_sel_hi:[1,0]
	v_pk_mul_f32 v[4:5], v[4:5], v[82:83] op_sel_hi:[1,0]
	s_waitcnt lgkmcnt(0)
	v_add_f32_e32 v38, v38, v39
	ds_bpermute_b32 v39, v94, v38
	s_waitcnt lgkmcnt(0)
	v_add_f32_e32 v38, v38, v39
	v_fmamk_f32 v38, v38, 0x3a800000, v205
	v_cmp_gt_f32_e32 vcc, s88, v38
	v_mul_f32_e32 v39, 0x4f800000, v38
	s_nop 0
	v_cndmask_b32_e32 v38, v38, v39, vcc
	v_sqrt_f32_e32 v39, v38
	s_nop 0
	v_add_u32_e32 v40, -1, v39
	v_fma_f32 v41, -v40, v39, v38
	v_cmp_ge_f32_e64 s[0:1], 0, v41
	v_add_u32_e32 v41, 1, v39
	s_nop 0
	v_cndmask_b32_e64 v40, v39, v40, s[0:1]
	v_fma_f32 v39, -v41, v39, v38
	v_cmp_lt_f32_e64 s[0:1], 0, v39
	s_nop 1
	v_cndmask_b32_e64 v39, v40, v41, s[0:1]
	v_mul_f32_e32 v40, 0x37800000, v39
	v_cndmask_b32_e32 v39, v39, v40, vcc
	v_cmp_class_f32_e32 vcc, v38, v206
	s_nop 1
	v_cndmask_b32_e32 v38, v39, v38, vcc
	v_div_scale_f32 v39, s[0:1], v38, v38, 1.0
	v_rcp_f32_e32 v40, v39
	s_nop 0
	v_fma_f32 v41, -v39, v40, 1.0
	v_fmac_f32_e32 v40, v41, v40
	v_div_scale_f32 v41, vcc, 1.0, v38, 1.0
	v_mul_f32_e32 v77, v41, v40
	v_fma_f32 v84, -v39, v77, v41
	v_fmac_f32_e32 v77, v84, v40
	v_fma_f32 v39, -v39, v77, v41
	v_div_fmas_f32 v39, v39, v40, v77
	v_div_fixup_f32 v84, v39, v38, 1.0
	s_waitcnt vmcnt(0)
	v_mul_f32_e32 v38, v6, v6
	v_mul_f32_e32 v39, v7, v7
	v_mov_b32_e32 v97, v38
	v_mov_b32_e32 v99, v39
	v_pk_add_f32 v[96:97], v[96:97], v[98:99]
	v_pk_fma_f32 v[98:99], v[22:23], v[22:23], v[86:87] op_sel_hi:[1,1,0]
	v_mul_f32_e32 v86, v25, v25
	v_mul_f32_e32 v40, v8, v8
	v_mul_f32_e32 v41, v9, v9
	v_pk_fma_f32 v[100:101], v[24:25], v[24:25], v[86:87] op_sel_hi:[1,1,0]
	v_mov_b32_e32 v99, v40
	v_mov_b32_e32 v101, v41
	v_pk_add_f32 v[98:99], v[98:99], v[100:101]
	v_pk_mul_f32 v[62:63], v[62:63], v[84:85] op_sel_hi:[1,0]
	v_pk_add_f32 v[96:97], v[96:97], v[98:99]
	v_pk_mul_f32 v[64:65], v[64:65], v[84:85] op_sel_hi:[1,0]
	v_add_f32_e32 v38, v96, v97
	ds_bpermute_b32 v39, v89, v38
	s_waitcnt lgkmcnt(0)
; __device__ __forceinline__ unsigned pk2(float lo, float hi) { return cvtpk(lo, hi); }
; template <int NR>
; __device__ __forceinline__ void norm_group(int m0, const float* src_lat, const float* src_ctx, bf16* H, const float* gain, const float* mod, int shoff, int scoff, int lane, const float* part, float* ctx_out) {
;     ...
;         rstd[i] = 1.0f / sqrtf(wave_sum(s) * (1.f / D) + EPS); }
;     const float* mr = mod + b * 6144;
; #pragma unroll
;     for (int j = 0; j < 4; ++j) { const int idx = 4 * (lane + 64 * j);
;         const f32x4 g = *(const f32x4*)(gain + idx), sc = *(const f32x4*)(mr + scoff + idx), sh = *(const f32x4*)(mr + shoff + idx);
;         const f32x4 gs = g * (1.f + sc);
; #pragma unroll
;         for (int i = 0; i < NR; ++i) { const f32x4 y = v[i][j] * rstd[i] * gs + sh;
;             v2u o; o.x = pk2(y.x, y.y); o.y = pk2(y.z, y.w);
;             *(v2u*)(H + (size_t)(m0 + i) * D + idx) = o; } }
	v_add_f32_e32 v38, v38, v39
	ds_bpermute_b32 v39, v90, v38
	s_waitcnt lgkmcnt(0)
	v_add_f32_e32 v38, v38, v39
	ds_bpermute_b32 v39, v91, v38
	s_waitcnt lgkmcnt(0)
	v_add_f32_e32 v38, v38, v39
	ds_bpermute_b32 v39, v92, v38
	s_waitcnt lgkmcnt(0)
	v_add_f32_e32 v38, v38, v39
	ds_bpermute_b32 v39, v93, v38
	s_waitcnt lgkmcnt(0)
	v_add_f32_e32 v38, v38, v39
	ds_bpermute_b32 v39, v94, v38
	s_waitcnt lgkmcnt(0)
	v_add_f32_e32 v38, v38, v39
	v_fmamk_f32 v38, v38, 0x3a800000, v205
	v_cmp_gt_f32_e32 vcc, s88, v38
	v_mul_f32_e32 v39, 0x4f800000, v38
	s_nop 0
	v_cndmask_b32_e32 v38, v38, v39, vcc
	v_sqrt_f32_e32 v39, v38
	s_nop 0
	v_add_u32_e32 v40, -1, v39
	v_fma_f32 v41, -v40, v39, v38
	v_cmp_ge_f32_e64 s[0:1], 0, v41
	v_add_u32_e32 v41, 1, v39
	s_nop 0
	v_cndmask_b32_e64 v40, v39, v40, s[0:1]
	v_fma_f32 v39, -v41, v39, v38
	v_cmp_lt_f32_e64 s[0:1], 0, v39
	s_nop 1
	v_cndmask_b32_e64 v39, v40, v41, s[0:1]
	v_mul_f32_e32 v40, 0x37800000, v39
	v_cndmask_b32_e32 v39, v39, v40, vcc
	v_cmp_class_f32_e32 vcc, v38, v206
	s_nop 1
	v_cndmask_b32_e32 v38, v39, v38, vcc
	v_div_scale_f32 v39, s[0:1], v38, v38, 1.0
	s_lshr_b32 s0, s20, 11
	s_mulk_i32 s0, 0x1800
	s_ashr_i32 s1, s0, 31
	s_lshl_b64 s[0:1], s[0:1], 2
	s_add_u32 s0, s21, s0
	s_addc_u32 s1, s22, s1
	s_add_u32 s2, s0, 0x1000
	s_addc_u32 s3, s1, 0
	global_load_dwordx4 v[96:99], v[78:79], off
	global_load_dwordx4 v[100:103], v76, s[2:3]
	global_load_dwordx4 v[104:107], v76, s[0:1]
	v_rcp_f32_e32 v40, v39
	s_add_i32 s10, s8, 1
	s_add_i32 s12, s8, 2
	s_add_i32 s16, s8, 3
	v_fma_f32 v41, -v39, v40, 1.0
	v_fmac_f32_e32 v40, v41, v40
	v_div_scale_f32 v41, vcc, 1.0, v38, 1.0
	v_mul_f32_e32 v77, v41, v40
	v_fma_f32 v86, -v39, v77, v41
	v_fmac_f32_e32 v77, v86, v40
	v_fma_f32 v39, -v39, v77, v41
	v_div_fmas_f32 v39, v39, v40, v77
	v_div_fixup_f32 v86, v39, v38, 1.0
	s_ashr_i32 s11, s10, 31
	s_ashr_i32 s13, s12, 31
	v_pk_mul_f32 v[58:59], v[58:59], v[86:87] op_sel_hi:[1,0]
	v_pk_mul_f32 v[60:61], v[60:61], v[86:87] op_sel_hi:[1,0]
	s_ashr_i32 s17, s16, 31
	s_lshl_b64 s[18:19], s[8:9], 11
	s_lshl_b64 s[10:11], s[10:11], 11
	s_lshl_b64 s[12:13], s[12:13], 11
	s_lshl_b64 s[16:17], s[16:17], 11
	v_lshlrev_b32_e32 v38, 1, v85
	v_pk_mul_f32 v[42:43], v[42:43], v[86:87] op_sel_hi:[1,0]
	v_pk_mul_f32 v[44:45], v[44:45], v[86:87] op_sel_hi:[1,0]
	s_waitcnt vmcnt(1)
	v_pk_add_f32 v[102:103], v[102:103], 1.0 op_sel_hi:[1,0]
	v_pk_add_f32 v[100:101], v[100:101], 1.0 op_sel_hi:[1,0]
	v_pk_mul_f32 v[98:99], v[98:99], v[102:103]
	v_pk_mul_f32 v[96:97], v[96:97], v[100:101]
	s_waitcnt vmcnt(0)
	v_pk_fma_f32 v[72:73], v[72:73], v[98:99], v[106:107]
	v_pk_fma_f32 v[70:71], v[70:71], v[96:97], v[104:105]
	v_pk_fma_f32 v[68:69], v[68:69], v[98:99], v[106:107]
	v_pk_fma_f32 v[66:67], v[66:67], v[96:97], v[104:105]
	v_pk_fma_f32 v[64:65], v[64:65], v[98:99], v[106:107]
	v_pk_fma_f32 v[62:63], v[62:63], v[96:97], v[104:105]
	v_pk_fma_f32 v[60:61], v[98:99], v[60:61], v[106:107]
	v_pk_fma_f32 v[58:59], v[96:97], v[58:59], v[104:105]
	v_cvt_pk_bf16_f32 v70, v70, v71
	v_cvt_pk_bf16_f32 v71, v72, v73
	v_lshl_add_u64 v[72:73], v[74:75], 0, s[18:19]
	v_cvt_pk_bf16_f32 v66, v66, v67
	v_cvt_pk_bf16_f32 v67, v68, v69
	v_lshl_add_u64 v[68:69], v[74:75], 0, s[10:11]
	v_cvt_pk_bf16_f32 v62, v62, v63
	v_cvt_pk_bf16_f32 v63, v64, v65
	v_lshl_add_u64 v[64:65], v[74:75], 0, s[12:13]
	v_cvt_pk_bf16_f32 v58, v58, v59
	v_cvt_pk_bf16_f32 v59, v60, v61
	v_lshl_add_u64 v[60:61], v[74:75], 0, s[16:17]
	global_store_dwordx2 v[72:73], v[70:71], off sc1
	global_store_dwordx2 v[68:69], v[66:67], off sc1
	global_store_dwordx2 v[64:65], v[62:63], off sc1
	global_store_dwordx2 v[60:61], v[58:59], off sc1
	v_lshlrev_b32_e32 v62, 2, v85
	global_load_dwordx4 v[58:61], v[78:79], off offset:1024
	s_nop 0
	global_load_dwordx4 v[62:65], v62, s[2:3]
	s_nop 0
	global_load_dwordx4 v[66:69], v76, s[0:1] offset:1024
	s_add_u32 s18, s90, s18
	s_addc_u32 s19, s91, s19
	s_add_u32 s10, s90, s10
	s_addc_u32 s11, s91, s11
	s_add_u32 s12, s90, s12
	s_addc_u32 s13, s91, s13
	s_add_u32 s16, s90, s16
	s_addc_u32 s17, s91, s17
	s_add_i32 s20, s20, s52
	s_add_i32 s8, s8, s59
	s_cmpk_gt_i32 s20, 0x1fff
	s_waitcnt vmcnt(1)
	v_pk_add_f32 v[62:63], v[62:63], 1.0 op_sel_hi:[1,0]
	v_pk_add_f32 v[64:65], v[64:65], 1.0 op_sel_hi:[1,0]
	v_pk_mul_f32 v[58:59], v[58:59], v[62:63]
	v_pk_mul_f32 v[60:61], v[60:61], v[64:65]
	s_waitcnt vmcnt(0)
; __device__ __forceinline__ unsigned pk2(float lo, float hi) { return cvtpk(lo, hi); }
; template <int NR>
; __device__ __forceinline__ void norm_group(int m0, const float* src_lat, const float* src_ctx, bf16* H, const float* gain, const float* mod, int shoff, int scoff, int lane, const float* part, float* ctx_out) {
;     ...
; #pragma unroll
;     for (int j = 0; j < 4; ++j) { const int idx = 4 * (lane + 64 * j);
;         const f32x4 g = *(const f32x4*)(gain + idx), sc = *(const f32x4*)(mr + scoff + idx), sh = *(const f32x4*)(mr + shoff + idx);
;         const f32x4 gs = g * (1.f + sc);
; #pragma unroll
;         for (int i = 0; i < NR; ++i) { const f32x4 y = v[i][j] * rstd[i] * gs + sh;
;             v2u o; o.x = pk2(y.x, y.y); o.y = pk2(y.z, y.w);
;             *(v2u*)(H + (size_t)(m0 + i) * D + idx) = o; } }
	v_pk_fma_f32 v[46:47], v[46:47], v[58:59], v[66:67]
	v_pk_fma_f32 v[48:49], v[48:49], v[60:61], v[68:69]
	v_cvt_pk_bf16_f32 v46, v46, v47
	v_pk_fma_f32 v[54:55], v[54:55], v[58:59], v[66:67]
	v_cvt_pk_bf16_f32 v47, v48, v49
	global_store_dwordx2 v38, v[46:47], s[10:11] sc1
	v_pk_mul_f32 v[46:47], v[50:51], v[84:85] op_sel_hi:[1,0]
	v_pk_mul_f32 v[48:49], v[52:53], v[84:85] op_sel_hi:[1,0]
	v_pk_fma_f32 v[46:47], v[46:47], v[58:59], v[66:67]
	v_pk_fma_f32 v[42:43], v[42:43], v[58:59], v[66:67]
	v_pk_fma_f32 v[56:57], v[56:57], v[60:61], v[68:69]
	v_cvt_pk_bf16_f32 v54, v54, v55
	v_pk_fma_f32 v[48:49], v[48:49], v[60:61], v[68:69]
	v_cvt_pk_bf16_f32 v55, v56, v57
	global_store_dwordx2 v38, v[54:55], s[18:19] sc1
	v_cvt_pk_bf16_f32 v46, v46, v47
	v_cvt_pk_bf16_f32 v47, v48, v49
	global_store_dwordx2 v38, v[46:47], s[12:13] sc1
	v_pk_fma_f32 v[44:45], v[44:45], v[60:61], v[68:69]
	v_cvt_pk_bf16_f32 v42, v42, v43
	s_nop 0
	v_cvt_pk_bf16_f32 v43, v44, v45
	global_store_dwordx2 v38, v[42:43], s[16:17] sc1
	v_lshlrev_b32_e32 v38, 2, v87
	global_load_dwordx4 v[42:45], v[78:79], off offset:2048
	global_load_dwordx4 v[46:49], v38, s[2:3]
	global_load_dwordx4 v[50:53], v76, s[0:1] offset:2048
	s_waitcnt vmcnt(1)
	v_pk_add_f32 v[48:49], v[48:49], 1.0 op_sel_hi:[1,0]
	v_pk_add_f32 v[46:47], v[46:47], 1.0 op_sel_hi:[1,0]
	v_pk_mul_f32 v[44:45], v[44:45], v[48:49]
	v_pk_mul_f32 v[42:43], v[42:43], v[46:47]
	s_waitcnt vmcnt(0)
	v_pk_fma_f32 v[32:33], v[32:33], v[44:45], v[52:53]
	v_pk_fma_f32 v[30:31], v[30:31], v[42:43], v[50:51]
	v_pk_fma_f32 v[18:19], v[18:19], v[42:43], v[50:51]
	v_cvt_pk_bf16_f32 v30, v30, v31
	v_cvt_pk_bf16_f32 v31, v32, v33
	v_lshlrev_b32_e32 v32, 1, v87
	v_pk_fma_f32 v[20:21], v[20:21], v[44:45], v[52:53]
	v_cvt_pk_bf16_f32 v18, v18, v19
	global_store_dwordx2 v32, v[30:31], s[18:19] sc1
	v_cvt_pk_bf16_f32 v19, v20, v21
	global_store_dwordx2 v32, v[18:19], s[10:11] sc1
	v_pk_mul_f32 v[18:19], v[26:27], v[84:85] op_sel_hi:[1,0]
	v_pk_mul_f32 v[20:21], v[28:29], v[84:85] op_sel_hi:[1,0]
	v_pk_fma_f32 v[18:19], v[18:19], v[42:43], v[50:51]
	v_pk_fma_f32 v[20:21], v[20:21], v[44:45], v[52:53]
	v_cvt_pk_bf16_f32 v18, v18, v19
	s_nop 0
	v_cvt_pk_bf16_f32 v19, v20, v21
	global_store_dwordx2 v32, v[18:19], s[12:13] sc1
	v_pk_mul_f32 v[18:19], v[22:23], v[86:87] op_sel_hi:[1,0]
	v_pk_mul_f32 v[20:21], v[24:25], v[86:87] op_sel_hi:[1,0]
	v_pk_fma_f32 v[18:19], v[18:19], v[42:43], v[50:51]
	v_pk_fma_f32 v[20:21], v[20:21], v[44:45], v[52:53]
	v_cvt_pk_bf16_f32 v18, v18, v19
	v_lshlrev_b32_e32 v22, 2, v88
	v_cvt_pk_bf16_f32 v19, v20, v21
	global_store_dwordx2 v32, v[18:19], s[16:17] sc1
	global_load_dwordx4 v[18:21], v[78:79], off offset:3072
	s_nop 0
	global_load_dwordx4 v[22:25], v22, s[2:3]
	s_nop 0
	global_load_dwordx4 v[26:29], v76, s[0:1] offset:3072
	s_waitcnt vmcnt(1)
	v_pk_add_f32 v[24:25], v[24:25], 1.0 op_sel_hi:[1,0]
	v_pk_add_f32 v[22:23], v[22:23], 1.0 op_sel_hi:[1,0]
	v_pk_mul_f32 v[20:21], v[20:21], v[24:25]
	v_pk_mul_f32 v[18:19], v[18:19], v[22:23]
	s_waitcnt vmcnt(0)
	v_pk_fma_f32 v[16:17], v[16:17], v[20:21], v[28:29]
	v_pk_fma_f32 v[14:15], v[14:15], v[18:19], v[26:27]
	v_pk_fma_f32 v[2:3], v[2:3], v[18:19], v[26:27]
	v_cvt_pk_bf16_f32 v14, v14, v15
	v_cvt_pk_bf16_f32 v15, v16, v17
	v_lshlrev_b32_e32 v16, 1, v88
	v_pk_fma_f32 v[4:5], v[4:5], v[20:21], v[28:29]
	v_cvt_pk_bf16_f32 v2, v2, v3
	global_store_dwordx2 v16, v[14:15], s[18:19] sc1
	v_cvt_pk_bf16_f32 v3, v4, v5
	global_store_dwordx2 v16, v[2:3], s[10:11] sc1
	v_pk_mul_f32 v[2:3], v[10:11], v[84:85] op_sel_hi:[1,0]
	v_pk_mul_f32 v[4:5], v[12:13], v[84:85] op_sel_hi:[1,0]
	v_pk_fma_f32 v[2:3], v[2:3], v[18:19], v[26:27]
	v_pk_fma_f32 v[4:5], v[4:5], v[20:21], v[28:29]
	v_cvt_pk_bf16_f32 v2, v2, v3
	s_nop 0
	v_cvt_pk_bf16_f32 v3, v4, v5
	global_store_dwordx2 v16, v[2:3], s[12:13] sc1
	v_pk_mul_f32 v[2:3], v[6:7], v[86:87] op_sel_hi:[1,0]
	v_pk_mul_f32 v[4:5], v[8:9], v[86:87] op_sel_hi:[1,0]
	v_pk_fma_f32 v[2:3], v[2:3], v[18:19], v[26:27]
	v_pk_fma_f32 v[4:5], v[4:5], v[20:21], v[28:29]
	v_cvt_pk_bf16_f32 v2, v2, v3
	s_nop 0
	v_cvt_pk_bf16_f32 v3, v4, v5
	global_store_dwordx2 v16, v[2:3], s[16:17] sc1
	s_cbranch_scc0 .LBB0_110

; __device__ __forceinline__ unsigned pk2(float lo, float hi) { return cvtpk(lo, hi); }
; template <int NR>
; __device__ __forceinline__ void norm_group(int m0, const float* src_lat, const float* src_ctx, bf16* H, const float* gain, const float* mod, int shoff, int scoff, int lane, const float* part, float* ctx_out) {
;     ...
;     for (int i = 0; i < NR; ++i) { float s = 0.f;
; #pragma unroll
;         for (int j = 0; j < 4; ++j) s += (v[i][j].x * v[i][j].x + v[i][j].y * v[i][j].y) + (v[i][j].z * v[i][j].z + v[i][j].w * v[i][j].w);
;         rstd[i] = 1.0f / sqrtf(wave_sum(s) * (1.f / D) + EPS); }
;     const float* mr = mod + b * 6144;
; #pragma unroll
;     for (int j = 0; j < 4; ++j) { const int idx = 4 * (lane + 64 * j);
;         const f32x4 g = *(const f32x4*)(gain + idx), sc = *(const f32x4*)(mr + scoff + idx), sh = *(const f32x4*)(mr + shoff + idx);
;         const f32x4 gs = g * (1.f + sc);
; #pragma unroll
;         for (int i = 0; i < NR; ++i) { const f32x4 y = v[i][j] * rstd[i] * gs + sh;
;             v2u o; o.x = pk2(y.x, y.y); o.y = pk2(y.z, y.w);
;             *(v2u*)(H + (size_t)(m0 + i) * D + idx) = o; } }
; __device__ __forceinline__ void norm_pass(const float* src_lat, const float* src_ctx, bf16* H, const float* gain, const float* mod, int shoff, int scoff, int nrows, int lane, int wave, const float* part = nullptr, float* ctx_out = nullptr) {
;     ...
;     for (int m = MLAT + gw; m < nrows; m += NGW) norm_group<1>(m, src_lat, src_ctx, H, gain, mod, shoff, scoff, lane, part, ctx_out);
.LBB0_113:
	s_min_i32 s0, s6, 0x8000
	s_ashr_i32 s0, s0, 13
	s_waitcnt vmcnt(3)
	v_pk_mul_f32 v[36:37], v[16:17], v[16:17]
	v_pk_mul_f32 v[42:43], v[14:15], v[14:15]
	s_mulk_i32 s0, 0x1800
	s_waitcnt vmcnt(2)
	v_pk_mul_f32 v[30:31], v[12:13], v[12:13]
	v_pk_mul_f32 v[32:33], v[10:11], v[10:11]
	v_pk_mov_b32 v[44:45], v[42:43], v[36:37] op_sel:[1,0]
	v_mov_b32_e32 v43, v37
	s_ashr_i32 s1, s0, 31
	v_pk_add_f32 v[36:37], v[44:45], v[42:43]
	v_pk_mov_b32 v[42:43], v[32:33], v[30:31] op_sel:[1,0]
	v_mov_b32_e32 v33, v31
	s_lshl_b64 s[0:1], s[0:1], 2
	v_readlane_b32 s6, v255, 4
	v_pk_add_f32 v[30:31], v[42:43], v[32:33]
	s_add_u32 s6, s6, s0
	v_readlane_b32 s0, v255, 3
	v_pk_add_f32 v[46:47], v[30:31], v[30:31] op_sel_hi:[0,1]
	s_waitcnt vmcnt(1)
	v_mul_f32_e32 v30, v6, v6
	s_addc_u32 s7, s0, s1
	v_pk_fma_f32 v[42:43], v[6:7], v[6:7], v[30:31] op_sel_hi:[1,1,0]
	v_mul_f32_e32 v30, v8, v8
	s_add_u32 s18, s6, 0x1000
	v_pk_fma_f32 v[44:45], v[8:9], v[8:9], v[30:31] op_sel_hi:[1,1,0]
	s_addc_u32 s19, s7, 0
	v_pk_add_f32 v[36:37], v[36:37], v[36:37] op_sel_hi:[0,1]
	s_waitcnt vmcnt(0)
	v_mul_f32_e32 v42, v2, v2
	v_mul_f32_e32 v44, v3, v3
	global_load_dwordx4 v[30:33], v18, s[18:19]
	v_mul_f32_e32 v36, v4, v4
	v_mul_f32_e32 v46, v5, v5
	v_pk_add_f32 v[50:51], v[42:43], v[44:45]
	global_load_dwordx4 v[42:45], v[20:21], off
	v_pk_add_f32 v[36:37], v[36:37], v[46:47]
	global_load_dwordx4 v[46:49], v18, s[6:7]
	v_pk_add_f32 v[36:37], v[50:51], v[36:37]
	s_add_i32 s78, s78, s52
	v_add_f32_e32 v19, v36, v37
	ds_bpermute_b32 v36, v24, v19
	s_waitcnt lgkmcnt(0)
	v_add_f32_e32 v19, v19, v36
	ds_bpermute_b32 v36, v25, v19
	s_waitcnt lgkmcnt(0)
	v_add_f32_e32 v19, v19, v36
	ds_bpermute_b32 v36, v26, v19
	s_waitcnt lgkmcnt(0)
	v_add_f32_e32 v19, v19, v36
	ds_bpermute_b32 v36, v27, v19
	s_waitcnt lgkmcnt(0)
	v_add_f32_e32 v19, v19, v36
	ds_bpermute_b32 v36, v28, v19
	s_waitcnt lgkmcnt(0)
	v_add_f32_e32 v19, v19, v36
	ds_bpermute_b32 v36, v29, v19
	s_waitcnt lgkmcnt(0)
	v_add_f32_e32 v19, v19, v36
	v_fmamk_f32 v19, v19, 0x3a800000, v205
	v_mul_f32_e32 v36, 0x4f800000, v19
	v_cmp_gt_f32_e32 vcc, s88, v19
	s_waitcnt vmcnt(2)
	v_pk_add_f32 v[30:31], v[30:31], 1.0 op_sel_hi:[1,0]
	v_cndmask_b32_e32 v19, v19, v36, vcc
	v_sqrt_f32_e32 v36, v19
	v_pk_add_f32 v[32:33], v[32:33], 1.0 op_sel_hi:[1,0]
	s_waitcnt vmcnt(1)
	v_pk_mul_f32 v[30:31], v[42:43], v[30:31]
	v_pk_mul_f32 v[32:33], v[44:45], v[32:33]
	v_add_u32_e32 v37, -1, v36
	v_add_u32_e32 v38, 1, v36
	v_fma_f32 v39, -v37, v36, v19
	v_fma_f32 v40, -v38, v36, v19
	v_cmp_ge_f32_e64 s[0:1], 0, v39
	s_nop 1
	v_cndmask_b32_e64 v36, v36, v37, s[0:1]
	v_cmp_lt_f32_e64 s[0:1], 0, v40
	s_nop 1
	v_cndmask_b32_e64 v36, v36, v38, s[0:1]
	v_mul_f32_e32 v37, 0x37800000, v36
	v_cndmask_b32_e32 v36, v36, v37, vcc
	v_cmp_class_f32_e32 vcc, v19, v206
	v_lshlrev_b32_e32 v38, 2, v85
	s_nop 0
	v_cndmask_b32_e32 v19, v36, v19, vcc
	v_div_scale_f32 v36, s[0:1], v19, v19, 1.0
	v_rcp_f32_e32 v37, v36
	v_div_scale_f32 v39, vcc, 1.0, v19, 1.0
	s_add_i32 s0, s78, 0x8000
	v_fma_f32 v40, -v36, v37, 1.0
	v_fmac_f32_e32 v37, v40, v37
	v_mul_f32_e32 v40, v39, v37
	v_fma_f32 v41, -v36, v40, v39
	v_fmac_f32_e32 v40, v41, v37
	v_fma_f32 v36, -v36, v40, v39
	v_div_fmas_f32 v36, v36, v37, v40
	v_div_fixup_f32 v36, v36, v19, 1.0
	v_pk_mul_f32 v[14:15], v[14:15], v[36:37] op_sel_hi:[1,0]
	v_pk_mul_f32 v[16:17], v[16:17], v[36:37] op_sel_hi:[1,0]
	s_waitcnt vmcnt(0)
	v_pk_fma_f32 v[14:15], v[30:31], v[14:15], v[46:47]
	v_pk_fma_f32 v[16:17], v[32:33], v[16:17], v[48:49]
	v_cvt_pk_bf16_f32 v14, v14, v15
	v_pk_mul_f32 v[10:11], v[10:11], v[36:37] op_sel_hi:[1,0]
	v_cvt_pk_bf16_f32 v15, v16, v17
	global_store_dwordx2 v[22:23], v[14:15], off sc1
	global_load_dwordx4 v[14:17], v38, s[18:19]
	s_nop 0
	global_load_dwordx4 v[30:33], v[20:21], off offset:1024
	global_load_dwordx4 v[42:45], v18, s[6:7] offset:1024
	v_pk_mul_f32 v[12:13], v[12:13], v[36:37] op_sel_hi:[1,0]
	v_lshlrev_b32_e32 v19, 2, v87
	v_pk_mul_f32 v[6:7], v[6:7], v[36:37] op_sel_hi:[1,0]
	v_pk_mul_f32 v[8:9], v[8:9], v[36:37] op_sel_hi:[1,0]
	s_add_u32 s2, s2, s52
	v_pk_mul_f32 v[2:3], v[2:3], v[36:37] op_sel_hi:[1,0]
	s_addc_u32 s3, s3, s53
	v_pk_mul_f32 v[4:5], v[4:5], v[36:37] op_sel_hi:[1,0]
	s_cmp_lt_i32 s0, 0x8400
	s_waitcnt vmcnt(2)
	v_pk_add_f32 v[14:15], v[14:15], 1.0 op_sel_hi:[1,0]
	v_pk_add_f32 v[16:17], v[16:17], 1.0 op_sel_hi:[1,0]
	s_waitcnt vmcnt(1)
	v_pk_mul_f32 v[14:15], v[30:31], v[14:15]
	v_pk_mul_f32 v[16:17], v[32:33], v[16:17]
	s_waitcnt vmcnt(0)
	v_pk_fma_f32 v[10:11], v[14:15], v[10:11], v[42:43]
	v_pk_fma_f32 v[12:13], v[16:17], v[12:13], v[44:45]
	v_cvt_pk_bf16_f32 v10, v10, v11
	s_nop 0
	v_cvt_pk_bf16_f32 v11, v12, v13
	global_store_dwordx2 v[22:23], v[10:11], off offset:512 sc1
	global_load_dwordx4 v[10:13], v19, s[18:19]
	s_nop 0
	global_load_dwordx4 v[14:17], v[20:21], off offset:2048
	global_load_dwordx4 v[30:33], v18, s[6:7] offset:2048
	v_lshlrev_b32_e32 v19, 2, v88
	s_waitcnt vmcnt(2)
	v_pk_add_f32 v[10:11], v[10:11], 1.0 op_sel_hi:[1,0]
	v_pk_add_f32 v[12:13], v[12:13], 1.0 op_sel_hi:[1,0]
	s_waitcnt vmcnt(1)
	v_pk_mul_f32 v[10:11], v[14:15], v[10:11]
	v_pk_mul_f32 v[12:13], v[16:17], v[12:13]
	s_waitcnt vmcnt(0)
	v_pk_fma_f32 v[6:7], v[6:7], v[10:11], v[30:31]
	v_pk_fma_f32 v[8:9], v[8:9], v[12:13], v[32:33]
	v_cvt_pk_bf16_f32 v6, v6, v7
	s_nop 0
	v_cvt_pk_bf16_f32 v7, v8, v9
	global_store_dwordx2 v[22:23], v[6:7], off offset:1024 sc1
	global_load_dwordx4 v[6:9], v19, s[18:19]
	s_nop 0
	global_load_dwordx4 v[10:13], v[20:21], off offset:3072
	global_load_dwordx4 v[14:17], v18, s[6:7] offset:3072
	s_waitcnt vmcnt(2)
	v_pk_add_f32 v[6:7], v[6:7], 1.0 op_sel_hi:[1,0]
	v_pk_add_f32 v[8:9], v[8:9], 1.0 op_sel_hi:[1,0]
	s_waitcnt vmcnt(1)
	v_pk_mul_f32 v[6:7], v[10:11], v[6:7]
	v_pk_mul_f32 v[8:9], v[12:13], v[8:9]
	s_waitcnt vmcnt(0)
	v_pk_fma_f32 v[2:3], v[2:3], v[6:7], v[14:15]
	v_pk_fma_f32 v[4:5], v[4:5], v[8:9], v[16:17]
	v_cvt_pk_bf16_f32 v2, v2, v3
	s_nop 0
	v_cvt_pk_bf16_f32 v3, v4, v5
	global_store_dwordx2 v[22:23], v[2:3], off offset:1536 sc1
	v_lshl_add_u64 v[22:23], v[22:23], 0, s[66:67]
	s_cbranch_scc0 .LBB0_118

; template <int NR>
; __device__ __forceinline__ void norm_group(int m0, const float* src_lat, const float* src_ctx, bf16* H, const float* gain, const float* mod, int shoff, int scoff, int lane, const float* part, float* ctx_out) {
;     ...
;     if (part && m0 >= MLAT) {
; #pragma unroll
;         for (int i = 0; i < NR; ++i)
; #pragma unroll
;             for (int j = 0; j < 4; ++j) { const size_t o = (size_t)(m0 - MLAT + i) * D + 4 * (lane + 64 * j);
;                 const f32x4 p0 = *(const f32x4*)(part + o), p1 = *(const f32x4*)(part + (size_t)MCTX * D + o), p2 = *(const f32x4*)(part + (size_t)2 * MCTX * D + o), p3 = *(const f32x4*)(part + (size_t)3 * MCTX * D + o);
;                 v[i][j] = v[i][j] + ((p0 + p1) + (p2 + p3)); *(f32x4*)(ctx_out + o) = v[i][j]; }
;     }
.LBB0_116:
	s_andn2_b64 vcc, exec, s[0:1]
	s_cbranch_vccnz .LBB0_113
	s_lshl_b64 s[0:1], s[78:79], 10
	v_mov_b32_e32 v31, s1
	v_or_b32_e32 v30, s0, v83
	v_lshlrev_b64 v[36:37], 2, v[30:31]
	v_lshl_add_u64 v[54:55], s[4:5], 0, v[36:37]
	v_lshl_add_u64 v[42:43], s[10:11], 0, v[36:37]
	v_lshl_add_u64 v[46:47], s[12:13], 0, v[36:37]
	v_lshl_add_u64 v[50:51], s[16:17], 0, v[36:37]
	global_load_dwordx4 v[30:33], v[54:55], off
	s_nop 0
	global_load_dwordx4 v[42:45], v[42:43], off
	s_nop 0
	global_load_dwordx4 v[46:49], v[46:47], off
	s_nop 0
	global_load_dwordx4 v[50:53], v[50:51], off
	v_mov_b32_e32 v57, s1
	v_or_b32_e32 v56, s0, v85
	v_lshl_add_u64 v[36:37], s[94:95], 0, v[36:37]
	v_lshlrev_b64 v[56:57], 2, v[56:57]
	v_lshl_add_u64 v[58:59], s[10:11], 0, v[56:57]
	v_lshl_add_u64 v[60:61], s[12:13], 0, v[56:57]
	v_lshl_add_u64 v[62:63], s[16:17], 0, v[56:57]
	v_lshl_add_u64 v[56:57], s[94:95], 0, v[56:57]
	s_waitcnt vmcnt(2)
	v_pk_add_f32 v[32:33], v[32:33], v[44:45]
	v_pk_add_f32 v[30:31], v[30:31], v[42:43]
	s_waitcnt vmcnt(0)
	v_pk_add_f32 v[42:43], v[48:49], v[52:53]
	v_pk_add_f32 v[44:45], v[46:47], v[50:51]
	v_pk_add_f32 v[32:33], v[32:33], v[42:43]
	v_pk_add_f32 v[30:31], v[30:31], v[44:45]
	v_pk_add_f32 v[16:17], v[16:17], v[32:33]
	v_pk_add_f32 v[14:15], v[14:15], v[30:31]
	global_store_dwordx4 v[36:37], v[14:17], off sc1
	global_load_dwordx4 v[30:33], v[54:55], off offset:1024
	global_load_dwordx4 v[42:45], v[58:59], off
	global_load_dwordx4 v[46:49], v[60:61], off
	global_load_dwordx4 v[50:53], v[62:63], off
	v_mov_b32_e32 v37, s1
	v_or_b32_e32 v36, s0, v87
	v_lshlrev_b64 v[36:37], 2, v[36:37]
	v_lshl_add_u64 v[58:59], s[10:11], 0, v[36:37]
	v_lshl_add_u64 v[60:61], s[12:13], 0, v[36:37]
	v_lshl_add_u64 v[62:63], s[16:17], 0, v[36:37]
	v_lshl_add_u64 v[36:37], s[94:95], 0, v[36:37]
	s_waitcnt vmcnt(2)
	v_pk_add_f32 v[32:33], v[32:33], v[44:45]
	v_pk_add_f32 v[30:31], v[30:31], v[42:43]
	s_waitcnt vmcnt(0)
	v_pk_add_f32 v[42:43], v[48:49], v[52:53]
	v_pk_add_f32 v[44:45], v[46:47], v[50:51]
	v_pk_add_f32 v[32:33], v[32:33], v[42:43]
	v_pk_add_f32 v[30:31], v[30:31], v[44:45]
	v_pk_add_f32 v[12:13], v[12:13], v[32:33]
	v_pk_add_f32 v[10:11], v[10:11], v[30:31]
	global_store_dwordx4 v[56:57], v[10:13], off sc1
	global_load_dwordx4 v[30:33], v[54:55], off offset:2048
	global_load_dwordx4 v[42:45], v[58:59], off
	global_load_dwordx4 v[46:49], v[60:61], off
	global_load_dwordx4 v[50:53], v[62:63], off
	v_mov_b32_e32 v57, s1
	v_or_b32_e32 v56, s0, v88
	v_lshlrev_b64 v[56:57], 2, v[56:57]
	v_lshl_add_u64 v[58:59], s[10:11], 0, v[56:57]
	v_lshl_add_u64 v[60:61], s[12:13], 0, v[56:57]
	v_lshl_add_u64 v[62:63], s[16:17], 0, v[56:57]
	s_waitcnt vmcnt(2)
	v_pk_add_f32 v[32:33], v[32:33], v[44:45]
	v_pk_add_f32 v[30:31], v[30:31], v[42:43]
	s_waitcnt vmcnt(0)
	v_pk_add_f32 v[42:43], v[48:49], v[52:53]
	v_pk_add_f32 v[44:45], v[46:47], v[50:51]
	v_pk_add_f32 v[32:33], v[32:33], v[42:43]
	v_pk_add_f32 v[30:31], v[30:31], v[44:45]
	v_pk_add_f32 v[8:9], v[8:9], v[32:33]
	v_pk_add_f32 v[6:7], v[6:7], v[30:31]
	global_store_dwordx4 v[36:37], v[6:9], off sc1
	global_load_dwordx4 v[30:33], v[54:55], off offset:3072
	global_load_dwordx4 v[42:45], v[58:59], off
	global_load_dwordx4 v[46:49], v[60:61], off
	global_load_dwordx4 v[50:53], v[62:63], off
	s_waitcnt vmcnt(2)
	v_pk_add_f32 v[32:33], v[32:33], v[44:45]
	v_pk_add_f32 v[30:31], v[30:31], v[42:43]
	s_waitcnt vmcnt(0)
	v_pk_add_f32 v[36:37], v[48:49], v[52:53]
	v_pk_add_f32 v[42:43], v[46:47], v[50:51]
	v_pk_add_f32 v[32:33], v[32:33], v[36:37]
	v_pk_add_f32 v[30:31], v[30:31], v[42:43]
	v_pk_add_f32 v[4:5], v[4:5], v[32:33]
	v_pk_add_f32 v[2:3], v[2:3], v[30:31]
	v_lshl_add_u64 v[30:31], s[94:95], 0, v[56:57]
	global_store_dwordx4 v[30:31], v[2:5], off sc1
	s_branch .LBB0_113

; template <int NR>
; __device__ __forceinline__ void norm_group(int m0, const float* src_lat, const float* src_ctx, bf16* H, const float* gain, const float* mod, int shoff, int scoff, int lane, const float* part, float* ctx_out) {
;     const float* xr = (m0 < MLAT) ? src_lat + (size_t)m0 * D : src_ctx + (size_t)(m0 - MLAT) * D;
;     const int b = (m0 < MLAT) ? (m0 >> 13) : 4;
;     f32x4 v[NR][4]; float rstd[NR];
; #pragma unroll
;     for (int i = 0; i < NR; ++i)
; #pragma unroll
;         for (int j = 0; j < 4; ++j) v[i][j] = *((const f32x4*)(xr + (size_t)i * D) + lane + 64 * j);
;     if (part && m0 >= MLAT) {
; #pragma unroll
;         for (int i = 0; i < NR; ++i)
; #pragma unroll
;             for (int j = 0; j < 4; ++j) { const size_t o = (size_t)(m0 - MLAT + i) * D + 4 * (lane + 64 * j);
;                 const f32x4 p0 = *(const f32x4*)(part + o), p1 = *(const f32x4*)(part + (size_t)MCTX * D + o), p2 = *(const f32x4*)(part + (size_t)2 * MCTX * D + o), p3 = *(const f32x4*)(part + (size_t)3 * MCTX * D + o);
;                 v[i][j] = v[i][j] + ((p0 + p1) + (p2 + p3)); *(f32x4*)(ctx_out + o) = v[i][j]; }
;     }
; #pragma unroll
;     for (int i = 0; i < NR; ++i) { float s = 0.f;
; #pragma unroll
;         for (int j = 0; j < 4; ++j) s += (v[i][j].x * v[i][j].x + v[i][j].y * v[i][j].y) + (v[i][j].z * v[i][j].z + v[i][j].w * v[i][j].w);
;         rstd[i] = 1.0f / sqrtf(wave_sum(s) * (1.f / D) + EPS); }
.LBB0_615:
	s_ashr_i32 s9, s8, 31
	s_lshl_b64 s[0:1], s[8:9], 12
	v_lshl_add_u64 v[6:7], v[76:77], 0, s[0:1]
	global_load_dwordx4 v[70:73], v[6:7], off
	global_load_dwordx4 v[54:57], v[6:7], off offset:1024
	global_load_dwordx4 v[30:33], v[6:7], off offset:2048
	global_load_dwordx4 v[14:17], v[6:7], off offset:3072
	v_add_co_u32_e32 v2, vcc, 0x1000, v6
	s_waitcnt vmcnt(3)
	v_pk_mul_f32 v[94:95], v[72:73], v[72:73]
	v_addc_co_u32_e32 v3, vcc, 0, v7, vcc
	global_load_dwordx4 v[66:69], v[2:3], off
	global_load_dwordx4 v[46:49], v[2:3], off offset:1024
	global_load_dwordx4 v[18:21], v[2:3], off offset:2048
	s_nop 0
	global_load_dwordx4 v[2:5], v[2:3], off offset:3072
	v_pk_mul_f32 v[96:97], v[70:71], v[70:71]
	s_waitcnt vmcnt(4)
	v_mul_f32_e32 v38, v14, v14
	v_pk_mov_b32 v[98:99], v[96:97], v[94:95] op_sel:[1,0]
	v_mov_b32_e32 v97, v95
	v_pk_add_f32 v[94:95], v[98:99], v[96:97]
	v_pk_mul_f32 v[96:97], v[56:57], v[56:57]
	v_pk_mul_f32 v[98:99], v[54:55], v[54:55]
	v_mul_f32_e32 v39, v15, v15
	v_pk_mov_b32 v[100:101], v[98:99], v[96:97] op_sel:[1,0]
	v_mov_b32_e32 v99, v97
	v_pk_add_f32 v[96:97], v[100:101], v[98:99]
	v_pk_add_f32 v[94:95], v[94:95], v[94:95] op_sel:[0,1] op_sel_hi:[1,0]
	v_pk_add_f32 v[96:97], v[96:97], v[96:97] op_sel:[0,1] op_sel_hi:[1,0]
	v_mov_b32_e32 v95, v38
	v_mov_b32_e32 v97, v39
	v_mul_f32_e32 v80, v31, v31
	v_pk_add_f32 v[94:95], v[94:95], v[96:97]
	v_pk_fma_f32 v[96:97], v[30:31], v[30:31], v[80:81] op_sel_hi:[1,1,0]
	v_mul_f32_e32 v80, v33, v33
	v_mul_f32_e32 v40, v16, v16
	v_mul_f32_e32 v41, v17, v17
	v_pk_fma_f32 v[98:99], v[32:33], v[32:33], v[80:81] op_sel_hi:[1,1,0]
	v_mov_b32_e32 v97, v40
	v_mov_b32_e32 v99, v41
	v_pk_add_f32 v[96:97], v[96:97], v[98:99]
	v_add_co_u32_e32 v8, vcc, s96, v6
	v_pk_add_f32 v[94:95], v[94:95], v[96:97]
	s_nop 0
	v_addc_co_u32_e32 v9, vcc, 0, v7, vcc
	v_add_f32_e32 v38, v94, v95
	ds_bpermute_b32 v39, v37, v38
	v_add_co_u32_e32 v6, vcc, s87, v6
	s_waitcnt lgkmcnt(0)
	v_add_f32_e32 v38, v38, v39
	ds_bpermute_b32 v39, v89, v38
	v_addc_co_u32_e32 v7, vcc, 0, v7, vcc
	global_load_dwordx4 v[62:65], v[6:7], off offset:-4096
	global_load_dwordx4 v[50:53], v[8:9], off offset:1024
	global_load_dwordx4 v[26:29], v[8:9], off offset:2048
	global_load_dwordx4 v[10:13], v[8:9], off offset:3072
	global_load_dwordx4 v[58:61], v[6:7], off
	global_load_dwordx4 v[42:45], v[6:7], off offset:1024
	global_load_dwordx4 v[22:25], v[6:7], off offset:2048
	s_nop 0
	global_load_dwordx4 v[6:9], v[6:7], off offset:3072
	s_waitcnt lgkmcnt(0)
	v_add_f32_e32 v38, v38, v39
	ds_bpermute_b32 v39, v90, v38
	s_waitcnt lgkmcnt(0)
	v_add_f32_e32 v38, v38, v39
	ds_bpermute_b32 v39, v91, v38
	s_waitcnt lgkmcnt(0)
	v_add_f32_e32 v38, v38, v39
	ds_bpermute_b32 v39, v92, v38
	s_waitcnt lgkmcnt(0)
	v_add_f32_e32 v38, v38, v39
	ds_bpermute_b32 v39, v93, v38
	s_waitcnt lgkmcnt(0)
	v_add_f32_e32 v38, v38, v39
	v_fmamk_f32 v38, v38, 0x3a800000, v205
	v_cmp_gt_f32_e32 vcc, s88, v38
	v_mul_f32_e32 v39, 0x4f800000, v38
	s_waitcnt vmcnt(11)
	v_pk_mul_f32 v[94:95], v[68:69], v[68:69]
	v_cndmask_b32_e32 v38, v38, v39, vcc
	v_sqrt_f32_e32 v39, v38
	v_pk_mul_f32 v[96:97], v[66:67], v[66:67]
	v_add_u32_e32 v40, -1, v39
	v_fma_f32 v41, -v40, v39, v38
	v_cmp_ge_f32_e64 s[0:1], 0, v41
	v_add_u32_e32 v41, 1, v39
	v_pk_mov_b32 v[98:99], v[96:97], v[94:95] op_sel:[1,0]
	v_cndmask_b32_e64 v40, v39, v40, s[0:1]
	v_fma_f32 v39, -v41, v39, v38
	v_cmp_lt_f32_e64 s[0:1], 0, v39
	v_mov_b32_e32 v97, v95
	v_pk_add_f32 v[94:95], v[98:99], v[96:97]
	v_cndmask_b32_e64 v39, v40, v41, s[0:1]
	v_mul_f32_e32 v40, 0x37800000, v39
	v_cndmask_b32_e32 v39, v39, v40, vcc
	v_cmp_class_f32_e32 vcc, v38, v206
	s_waitcnt vmcnt(10)
	v_pk_mul_f32 v[96:97], v[48:49], v[48:49]
	v_pk_mul_f32 v[98:99], v[46:47], v[46:47]
	v_cndmask_b32_e32 v38, v39, v38, vcc
	v_div_scale_f32 v39, s[0:1], v38, v38, 1.0
	v_rcp_f32_e32 v40, v39
	v_pk_mov_b32 v[100:101], v[98:99], v[96:97] op_sel:[1,0]
	v_mov_b32_e32 v99, v97
	v_pk_add_f32 v[96:97], v[100:101], v[98:99]
	v_fma_f32 v41, -v39, v40, 1.0
	v_fmac_f32_e32 v40, v41, v40
	v_div_scale_f32 v41, vcc, 1.0, v38, 1.0
	v_mul_f32_e32 v80, v41, v40
	v_fma_f32 v82, -v39, v80, v41
	v_fmac_f32_e32 v80, v82, v40
	v_fma_f32 v39, -v39, v80, v41
	v_div_fmas_f32 v39, v39, v40, v80
	v_div_fixup_f32 v80, v39, v38, 1.0
	s_waitcnt vmcnt(8)
	v_mul_f32_e32 v38, v2, v2
	v_mul_f32_e32 v39, v3, v3
	v_pk_add_f32 v[94:95], v[94:95], v[94:95] op_sel:[0,1] op_sel_hi:[1,0]
	v_pk_add_f32 v[96:97], v[96:97], v[96:97] op_sel:[0,1] op_sel_hi:[1,0]
	v_mov_b32_e32 v95, v38
	v_mov_b32_e32 v97, v39
	v_mul_f32_e32 v82, v19, v19
	v_pk_add_f32 v[94:95], v[94:95], v[96:97]
	v_pk_fma_f32 v[96:97], v[18:19], v[18:19], v[82:83] op_sel_hi:[1,1,0]
	v_mul_f32_e32 v82, v21, v21
	v_mul_f32_e32 v40, v4, v4
	v_mul_f32_e32 v41, v5, v5
	v_pk_fma_f32 v[98:99], v[20:21], v[20:21], v[82:83] op_sel_hi:[1,1,0]
	v_mov_b32_e32 v97, v40
	v_mov_b32_e32 v99, v41
	v_pk_add_f32 v[96:97], v[96:97], v[98:99]
	v_pk_mul_f32 v[70:71], v[70:71], v[80:81] op_sel_hi:[1,0]
	v_pk_add_f32 v[94:95], v[94:95], v[96:97]
	s_waitcnt vmcnt(7)
	v_pk_mul_f32 v[96:97], v[62:63], v[62:63]
	v_add_f32_e32 v38, v94, v95
	ds_bpermute_b32 v39, v37, v38
	v_pk_mul_f32 v[94:95], v[64:65], v[64:65]
	v_pk_mul_f32 v[72:73], v[72:73], v[80:81] op_sel_hi:[1,0]
	v_pk_mov_b32 v[98:99], v[96:97], v[94:95] op_sel:[1,0]
	v_mov_b32_e32 v97, v95
	s_waitcnt lgkmcnt(0)
	v_add_f32_e32 v38, v38, v39
	ds_bpermute_b32 v39, v89, v38
	v_pk_add_f32 v[94:95], v[98:99], v[96:97]
	s_waitcnt vmcnt(6)
	v_pk_mul_f32 v[96:97], v[52:53], v[52:53]
	v_pk_mul_f32 v[98:99], v[50:51], v[50:51]
	v_pk_add_f32 v[94:95], v[94:95], v[94:95] op_sel:[0,1] op_sel_hi:[1,0]
	s_waitcnt lgkmcnt(0)
; template <int NR>
; __device__ __forceinline__ void norm_group(int m0, const float* src_lat, const float* src_ctx, bf16* H, const float* gain, const float* mod, int shoff, int scoff, int lane, const float* part, float* ctx_out) {
;     ...
;     for (int i = 0; i < NR; ++i) { float s = 0.f;
; #pragma unroll
;         for (int j = 0; j < 4; ++j) s += (v[i][j].x * v[i][j].x + v[i][j].y * v[i][j].y) + (v[i][j].z * v[i][j].z + v[i][j].w * v[i][j].w);
;         rstd[i] = 1.0f / sqrtf(wave_sum(s) * (1.f / D) + EPS); }
;     ...
;         for (int i = 0; i < NR; ++i) { const f32x4 y = v[i][j] * rstd[i] * gs + sh;
	v_add_f32_e32 v38, v38, v39
	ds_bpermute_b32 v39, v90, v38
	v_pk_mov_b32 v[100:101], v[98:99], v[96:97] op_sel:[1,0]
	v_mov_b32_e32 v99, v97
	v_pk_add_f32 v[96:97], v[100:101], v[98:99]
	v_pk_mul_f32 v[54:55], v[54:55], v[80:81] op_sel_hi:[1,0]
	s_waitcnt lgkmcnt(0)
	v_add_f32_e32 v38, v38, v39
	ds_bpermute_b32 v39, v91, v38
	v_pk_add_f32 v[96:97], v[96:97], v[96:97] op_sel:[0,1] op_sel_hi:[1,0]
	v_pk_mul_f32 v[56:57], v[56:57], v[80:81] op_sel_hi:[1,0]
	v_pk_mul_f32 v[30:31], v[30:31], v[80:81] op_sel_hi:[1,0]
	v_pk_mul_f32 v[32:33], v[32:33], v[80:81] op_sel_hi:[1,0]
	s_waitcnt lgkmcnt(0)
	v_add_f32_e32 v38, v38, v39
	ds_bpermute_b32 v39, v92, v38
	v_pk_mul_f32 v[14:15], v[14:15], v[80:81] op_sel_hi:[1,0]
	v_pk_mul_f32 v[16:17], v[16:17], v[80:81] op_sel_hi:[1,0]
	s_waitcnt lgkmcnt(0)
	v_add_f32_e32 v38, v38, v39
	ds_bpermute_b32 v39, v93, v38
	s_waitcnt lgkmcnt(0)
	v_add_f32_e32 v38, v38, v39
	v_fmamk_f32 v38, v38, 0x3a800000, v205
	v_cmp_gt_f32_e32 vcc, s88, v38
	v_mul_f32_e32 v39, 0x4f800000, v38
	s_nop 0
	v_cndmask_b32_e32 v38, v38, v39, vcc
	v_sqrt_f32_e32 v39, v38
	s_nop 0
	v_add_u32_e32 v40, -1, v39
	v_fma_f32 v41, -v40, v39, v38
	v_cmp_ge_f32_e64 s[0:1], 0, v41
	v_add_u32_e32 v41, 1, v39
	s_nop 0
	v_cndmask_b32_e64 v40, v39, v40, s[0:1]
	v_fma_f32 v39, -v41, v39, v38
	v_cmp_lt_f32_e64 s[0:1], 0, v39
	s_nop 1
	v_cndmask_b32_e64 v39, v40, v41, s[0:1]
	v_mul_f32_e32 v40, 0x37800000, v39
	v_cndmask_b32_e32 v39, v39, v40, vcc
	v_cmp_class_f32_e32 vcc, v38, v206
	s_nop 1
	v_cndmask_b32_e32 v38, v39, v38, vcc
	v_div_scale_f32 v39, s[0:1], v38, v38, 1.0
	v_rcp_f32_e32 v40, v39
	s_nop 0
	v_fma_f32 v41, -v39, v40, 1.0
	v_fmac_f32_e32 v40, v41, v40
	v_div_scale_f32 v41, vcc, 1.0, v38, 1.0
	v_mul_f32_e32 v82, v41, v40
	v_fma_f32 v84, -v39, v82, v41
	v_fmac_f32_e32 v82, v84, v40
	v_fma_f32 v39, -v39, v82, v41
	v_div_fmas_f32 v39, v39, v40, v82
	v_div_fixup_f32 v82, v39, v38, 1.0
	s_waitcnt vmcnt(4)
	v_mul_f32_e32 v38, v10, v10
	v_mul_f32_e32 v39, v11, v11
	v_mov_b32_e32 v95, v38
	v_mov_b32_e32 v97, v39
	v_mul_f32_e32 v84, v27, v27
	v_pk_add_f32 v[94:95], v[94:95], v[96:97]
	v_pk_fma_f32 v[96:97], v[26:27], v[26:27], v[84:85] op_sel_hi:[1,1,0]
	v_mul_f32_e32 v84, v29, v29
	v_mul_f32_e32 v40, v12, v12
	v_mul_f32_e32 v41, v13, v13
	v_pk_fma_f32 v[98:99], v[28:29], v[28:29], v[84:85] op_sel_hi:[1,1,0]
	v_mov_b32_e32 v97, v40
	v_mov_b32_e32 v99, v41
	v_pk_add_f32 v[96:97], v[96:97], v[98:99]
	v_pk_mul_f32 v[66:67], v[66:67], v[82:83] op_sel_hi:[1,0]
	v_pk_add_f32 v[94:95], v[94:95], v[96:97]
	s_waitcnt vmcnt(3)
	v_pk_mul_f32 v[96:97], v[58:59], v[58:59]
	v_add_f32_e32 v38, v94, v95
	ds_bpermute_b32 v39, v37, v38
	v_pk_mul_f32 v[94:95], v[60:61], v[60:61]
	v_pk_mul_f32 v[68:69], v[68:69], v[82:83] op_sel_hi:[1,0]
	v_pk_mov_b32 v[98:99], v[96:97], v[94:95] op_sel:[1,0]
	v_mov_b32_e32 v97, v95
	s_waitcnt lgkmcnt(0)
	v_add_f32_e32 v38, v38, v39
	ds_bpermute_b32 v39, v89, v38
	v_pk_add_f32 v[94:95], v[98:99], v[96:97]
	s_waitcnt vmcnt(2)
	v_pk_mul_f32 v[96:97], v[44:45], v[44:45]
	v_pk_mul_f32 v[98:99], v[42:43], v[42:43]
	v_pk_add_f32 v[94:95], v[94:95], v[94:95] op_sel:[0,1] op_sel_hi:[1,0]
	s_waitcnt lgkmcnt(0)
	v_add_f32_e32 v38, v38, v39
	ds_bpermute_b32 v39, v90, v38
	v_pk_mov_b32 v[100:101], v[98:99], v[96:97] op_sel:[1,0]
	v_mov_b32_e32 v99, v97
	v_pk_add_f32 v[96:97], v[100:101], v[98:99]
	v_pk_mul_f32 v[46:47], v[46:47], v[82:83] op_sel_hi:[1,0]
	s_waitcnt lgkmcnt(0)
	v_add_f32_e32 v38, v38, v39
	ds_bpermute_b32 v39, v91, v38
	v_pk_add_f32 v[96:97], v[96:97], v[96:97] op_sel:[0,1] op_sel_hi:[1,0]
	v_pk_mul_f32 v[48:49], v[48:49], v[82:83] op_sel_hi:[1,0]
	v_pk_mul_f32 v[18:19], v[18:19], v[82:83] op_sel_hi:[1,0]
	v_pk_mul_f32 v[20:21], v[20:21], v[82:83] op_sel_hi:[1,0]
	s_waitcnt lgkmcnt(0)
	v_add_f32_e32 v38, v38, v39
	ds_bpermute_b32 v39, v92, v38
	v_pk_mul_f32 v[2:3], v[2:3], v[82:83] op_sel_hi:[1,0]
	v_pk_mul_f32 v[4:5], v[4:5], v[82:83] op_sel_hi:[1,0]
	s_waitcnt lgkmcnt(0)
	v_add_f32_e32 v38, v38, v39
	ds_bpermute_b32 v39, v93, v38
	s_waitcnt lgkmcnt(0)
	v_add_f32_e32 v38, v38, v39
	v_fmamk_f32 v38, v38, 0x3a800000, v205
	v_cmp_gt_f32_e32 vcc, s88, v38
	v_mul_f32_e32 v39, 0x4f800000, v38
	s_nop 0
	v_cndmask_b32_e32 v38, v38, v39, vcc
	v_sqrt_f32_e32 v39, v38
	s_nop 0
	v_add_u32_e32 v40, -1, v39
	v_fma_f32 v41, -v40, v39, v38
	v_cmp_ge_f32_e64 s[0:1], 0, v41
	v_add_u32_e32 v41, 1, v39
	s_nop 0
	v_cndmask_b32_e64 v40, v39, v40, s[0:1]
	v_fma_f32 v39, -v41, v39, v38
	v_cmp_lt_f32_e64 s[0:1], 0, v39
	s_nop 1
	v_cndmask_b32_e64 v39, v40, v41, s[0:1]
	v_mul_f32_e32 v40, 0x37800000, v39
	v_cndmask_b32_e32 v39, v39, v40, vcc
	v_cmp_class_f32_e32 vcc, v38, v206
	s_nop 1
	v_cndmask_b32_e32 v38, v39, v38, vcc
	v_div_scale_f32 v39, s[0:1], v38, v38, 1.0
	v_rcp_f32_e32 v40, v39
	s_nop 0
	v_fma_f32 v41, -v39, v40, 1.0
	v_fmac_f32_e32 v40, v41, v40
	v_div_scale_f32 v41, vcc, 1.0, v38, 1.0
	v_mul_f32_e32 v84, v41, v40
	v_fma_f32 v86, -v39, v84, v41
	v_fmac_f32_e32 v84, v86, v40
	v_fma_f32 v39, -v39, v84, v41
	v_div_fmas_f32 v39, v39, v40, v84
	v_div_fixup_f32 v84, v39, v38, 1.0
	s_waitcnt vmcnt(0)
	v_mul_f32_e32 v38, v6, v6
	v_mul_f32_e32 v39, v7, v7
	v_mov_b32_e32 v95, v38
	v_mov_b32_e32 v97, v39
	v_mul_f32_e32 v86, v23, v23
	v_pk_add_f32 v[94:95], v[94:95], v[96:97]
	v_pk_fma_f32 v[96:97], v[22:23], v[22:23], v[86:87] op_sel_hi:[1,1,0]
	v_mul_f32_e32 v86, v25, v25
	v_mul_f32_e32 v40, v8, v8
	v_mul_f32_e32 v41, v9, v9
	v_pk_fma_f32 v[98:99], v[24:25], v[24:25], v[86:87] op_sel_hi:[1,1,0]
	v_mov_b32_e32 v97, v40
	v_mov_b32_e32 v99, v41
	v_pk_add_f32 v[96:97], v[96:97], v[98:99]
	v_pk_mul_f32 v[62:63], v[62:63], v[84:85] op_sel_hi:[1,0]
	v_pk_add_f32 v[94:95], v[94:95], v[96:97]
	v_pk_mul_f32 v[64:65], v[64:65], v[84:85] op_sel_hi:[1,0]
	v_add_f32_e32 v38, v94, v95
	ds_bpermute_b32 v39, v37, v38
	s_waitcnt lgkmcnt(0)
; __device__ __forceinline__ unsigned pk2(float lo, float hi) { return cvtpk(lo, hi); }
; template <int NR>
; __device__ __forceinline__ void norm_group(int m0, const float* src_lat, const float* src_ctx, bf16* H, const float* gain, const float* mod, int shoff, int scoff, int lane, const float* part, float* ctx_out) {
;     ...
;         rstd[i] = 1.0f / sqrtf(wave_sum(s) * (1.f / D) + EPS); }
;     const float* mr = mod + b * 6144;
; #pragma unroll
;     for (int j = 0; j < 4; ++j) { const int idx = 4 * (lane + 64 * j);
;         const f32x4 g = *(const f32x4*)(gain + idx), sc = *(const f32x4*)(mr + scoff + idx), sh = *(const f32x4*)(mr + shoff + idx);
;         const f32x4 gs = g * (1.f + sc);
; #pragma unroll
;         for (int i = 0; i < NR; ++i) { const f32x4 y = v[i][j] * rstd[i] * gs + sh;
;             v2u o; o.x = pk2(y.x, y.y); o.y = pk2(y.z, y.w);
;             *(v2u*)(H + (size_t)(m0 + i) * D + idx) = o; } }
	v_add_f32_e32 v38, v38, v39
	ds_bpermute_b32 v39, v89, v38
	s_waitcnt lgkmcnt(0)
	v_add_f32_e32 v38, v38, v39
	ds_bpermute_b32 v39, v90, v38
	s_waitcnt lgkmcnt(0)
	v_add_f32_e32 v38, v38, v39
	ds_bpermute_b32 v39, v91, v38
	s_waitcnt lgkmcnt(0)
	v_add_f32_e32 v38, v38, v39
	ds_bpermute_b32 v39, v92, v38
	s_waitcnt lgkmcnt(0)
	v_add_f32_e32 v38, v38, v39
	ds_bpermute_b32 v39, v93, v38
	s_waitcnt lgkmcnt(0)
	v_add_f32_e32 v38, v38, v39
	v_fmamk_f32 v38, v38, 0x3a800000, v205
	v_cmp_gt_f32_e32 vcc, s88, v38
	v_mul_f32_e32 v39, 0x4f800000, v38
	s_nop 0
	v_cndmask_b32_e32 v38, v38, v39, vcc
	v_sqrt_f32_e32 v39, v38
	s_nop 0
	v_add_u32_e32 v40, -1, v39
	v_fma_f32 v41, -v40, v39, v38
	v_cmp_ge_f32_e64 s[0:1], 0, v41
	v_add_u32_e32 v41, 1, v39
	s_nop 0
	v_cndmask_b32_e64 v40, v39, v40, s[0:1]
	v_fma_f32 v39, -v41, v39, v38
	v_cmp_lt_f32_e64 s[0:1], 0, v39
	s_nop 1
	v_cndmask_b32_e64 v39, v40, v41, s[0:1]
	v_mul_f32_e32 v40, 0x37800000, v39
	v_cndmask_b32_e32 v39, v39, v40, vcc
	v_cmp_class_f32_e32 vcc, v38, v206
	s_nop 1
	v_cndmask_b32_e32 v38, v39, v38, vcc
	v_div_scale_f32 v39, s[0:1], v38, v38, 1.0
	s_lshr_b32 s0, s18, 11
	v_rcp_f32_e32 v40, v39
	s_mulk_i32 s0, 0x1800
	s_ashr_i32 s1, s0, 31
	s_lshl_b64 s[0:1], s[0:1], 2
	s_add_u32 s0, s72, s0
	v_fma_f32 v41, -v39, v40, 1.0
	s_addc_u32 s1, s74, s1
	v_fmac_f32_e32 v40, v41, v40
	v_div_scale_f32 v41, vcc, 1.0, v38, 1.0
	s_add_u32 s2, s0, 0x4000
	v_mul_f32_e32 v86, v41, v40
	s_addc_u32 s3, s1, 0
	v_fma_f32 v94, -v39, v86, v41
	s_add_u32 s0, s0, 0x3000
	v_fmac_f32_e32 v86, v94, v40
	s_addc_u32 s1, s1, 0
	global_load_dwordx4 v[94:97], v[78:79], off
	global_load_dwordx4 v[98:101], v34, s[2:3]
	global_load_dwordx4 v[102:105], v34, s[0:1]
	v_fma_f32 v39, -v39, v86, v41
	v_div_fmas_f32 v39, v39, v40, v86
	v_div_fixup_f32 v86, v39, v38, 1.0
	s_add_i32 s10, s8, 1
	s_add_i32 s12, s8, 2
	s_add_i32 s14, s8, 3
	s_ashr_i32 s11, s10, 31
	s_ashr_i32 s13, s12, 31
	v_pk_mul_f32 v[58:59], v[58:59], v[86:87] op_sel_hi:[1,0]
	v_pk_mul_f32 v[60:61], v[60:61], v[86:87] op_sel_hi:[1,0]
	s_ashr_i32 s15, s14, 31
	s_lshl_b64 s[16:17], s[8:9], 11
	s_lshl_b64 s[10:11], s[10:11], 11
	s_lshl_b64 s[12:13], s[12:13], 11
	s_lshl_b64 s[14:15], s[14:15], 11
	v_lshlrev_b32_e32 v38, 1, v83
	v_pk_mul_f32 v[42:43], v[42:43], v[86:87] op_sel_hi:[1,0]
	v_pk_mul_f32 v[44:45], v[44:45], v[86:87] op_sel_hi:[1,0]
	s_waitcnt vmcnt(1)
	v_pk_add_f32 v[100:101], v[100:101], 1.0 op_sel_hi:[1,0]
	v_pk_add_f32 v[98:99], v[98:99], 1.0 op_sel_hi:[1,0]
	v_pk_mul_f32 v[96:97], v[96:97], v[100:101]
	v_pk_mul_f32 v[94:95], v[94:95], v[98:99]
	s_waitcnt vmcnt(0)
	v_pk_fma_f32 v[72:73], v[72:73], v[96:97], v[104:105]
	v_pk_fma_f32 v[70:71], v[70:71], v[94:95], v[102:103]
	v_pk_fma_f32 v[68:69], v[68:69], v[96:97], v[104:105]
	v_pk_fma_f32 v[66:67], v[66:67], v[94:95], v[102:103]
	v_pk_fma_f32 v[64:65], v[64:65], v[96:97], v[104:105]
	v_pk_fma_f32 v[62:63], v[62:63], v[94:95], v[102:103]
	v_pk_fma_f32 v[60:61], v[96:97], v[60:61], v[104:105]
	v_pk_fma_f32 v[58:59], v[94:95], v[58:59], v[102:103]
	v_cvt_pk_bf16_f32 v70, v70, v71
	v_cvt_pk_bf16_f32 v71, v72, v73
	v_lshl_add_u64 v[72:73], v[74:75], 0, s[16:17]
	v_cvt_pk_bf16_f32 v66, v66, v67
	v_cvt_pk_bf16_f32 v67, v68, v69
	v_lshl_add_u64 v[68:69], v[74:75], 0, s[10:11]
	v_cvt_pk_bf16_f32 v62, v62, v63
	v_cvt_pk_bf16_f32 v63, v64, v65
	v_lshl_add_u64 v[64:65], v[74:75], 0, s[12:13]
	v_cvt_pk_bf16_f32 v58, v58, v59
	v_cvt_pk_bf16_f32 v59, v60, v61
	v_lshl_add_u64 v[60:61], v[74:75], 0, s[14:15]
	global_store_dwordx2 v[72:73], v[70:71], off sc1
	global_store_dwordx2 v[68:69], v[66:67], off sc1
	global_store_dwordx2 v[64:65], v[62:63], off sc1
	global_store_dwordx2 v[60:61], v[58:59], off sc1
	v_lshlrev_b32_e32 v62, 2, v83
	global_load_dwordx4 v[58:61], v[78:79], off offset:1024
	global_load_dwordx4 v[64:67], v62, s[2:3]
	global_load_dwordx4 v[68:71], v62, s[0:1]
	s_add_u32 s16, s90, s16
	s_addc_u32 s17, s91, s17
	s_add_u32 s10, s90, s10
	s_addc_u32 s11, s91, s11
	s_add_u32 s12, s90, s12
	s_addc_u32 s13, s91, s13
	s_add_u32 s14, s90, s14
	s_addc_u32 s15, s91, s15
	s_add_i32 s18, s18, s52
	s_add_i32 s8, s8, s59
	s_cmpk_gt_i32 s18, 0x1fff
	s_waitcnt vmcnt(1)
; __device__ __forceinline__ unsigned pk2(float lo, float hi) { return cvtpk(lo, hi); }
; template <int NR>
; __device__ __forceinline__ void norm_group(int m0, const float* src_lat, const float* src_ctx, bf16* H, const float* gain, const float* mod, int shoff, int scoff, int lane, const float* part, float* ctx_out) {
;     ...
; #pragma unroll
;     for (int j = 0; j < 4; ++j) { const int idx = 4 * (lane + 64 * j);
;         const f32x4 g = *(const f32x4*)(gain + idx), sc = *(const f32x4*)(mr + scoff + idx), sh = *(const f32x4*)(mr + shoff + idx);
;         const f32x4 gs = g * (1.f + sc);
; #pragma unroll
;         for (int i = 0; i < NR; ++i) { const f32x4 y = v[i][j] * rstd[i] * gs + sh;
;             v2u o; o.x = pk2(y.x, y.y); o.y = pk2(y.z, y.w);
;             *(v2u*)(H + (size_t)(m0 + i) * D + idx) = o; } }
	v_pk_add_f32 v[64:65], v[64:65], 1.0 op_sel_hi:[1,0]
	v_pk_add_f32 v[62:63], v[66:67], 1.0 op_sel_hi:[1,0]
	v_pk_mul_f32 v[58:59], v[58:59], v[64:65]
	v_pk_mul_f32 v[60:61], v[60:61], v[62:63]
	s_waitcnt vmcnt(0)
	v_pk_fma_f32 v[46:47], v[46:47], v[58:59], v[68:69]
	v_pk_fma_f32 v[48:49], v[48:49], v[60:61], v[70:71]
	v_cvt_pk_bf16_f32 v46, v46, v47
	v_pk_fma_f32 v[54:55], v[54:55], v[58:59], v[68:69]
	v_cvt_pk_bf16_f32 v47, v48, v49
	global_store_dwordx2 v38, v[46:47], s[10:11] sc1
	v_pk_mul_f32 v[46:47], v[50:51], v[84:85] op_sel_hi:[1,0]
	v_pk_mul_f32 v[48:49], v[52:53], v[84:85] op_sel_hi:[1,0]
	v_pk_fma_f32 v[46:47], v[46:47], v[58:59], v[68:69]
	v_pk_fma_f32 v[42:43], v[42:43], v[58:59], v[68:69]
	v_pk_fma_f32 v[56:57], v[56:57], v[60:61], v[70:71]
	v_cvt_pk_bf16_f32 v54, v54, v55
	v_pk_fma_f32 v[48:49], v[48:49], v[60:61], v[70:71]
	v_cvt_pk_bf16_f32 v55, v56, v57
	global_store_dwordx2 v38, v[54:55], s[16:17] sc1
	v_cvt_pk_bf16_f32 v46, v46, v47
	v_cvt_pk_bf16_f32 v47, v48, v49
	global_store_dwordx2 v38, v[46:47], s[12:13] sc1
	v_pk_fma_f32 v[44:45], v[44:45], v[60:61], v[70:71]
	v_cvt_pk_bf16_f32 v42, v42, v43
	s_nop 0
	v_cvt_pk_bf16_f32 v43, v44, v45
	global_store_dwordx2 v38, v[42:43], s[14:15] sc1
	v_lshlrev_b32_e32 v38, 2, v85
	global_load_dwordx4 v[42:45], v[78:79], off offset:2048
	global_load_dwordx4 v[46:49], v38, s[2:3]
	global_load_dwordx4 v[50:53], v38, s[0:1]
	s_waitcnt vmcnt(1)
	v_pk_add_f32 v[48:49], v[48:49], 1.0 op_sel_hi:[1,0]
	v_pk_add_f32 v[46:47], v[46:47], 1.0 op_sel_hi:[1,0]
	v_pk_mul_f32 v[44:45], v[44:45], v[48:49]
	v_pk_mul_f32 v[42:43], v[42:43], v[46:47]
	s_waitcnt vmcnt(0)
	v_pk_fma_f32 v[32:33], v[32:33], v[44:45], v[52:53]
	v_pk_fma_f32 v[30:31], v[30:31], v[42:43], v[50:51]
	v_pk_fma_f32 v[18:19], v[18:19], v[42:43], v[50:51]
	v_cvt_pk_bf16_f32 v30, v30, v31
	v_cvt_pk_bf16_f32 v31, v32, v33
	v_lshlrev_b32_e32 v32, 1, v85
	v_pk_fma_f32 v[20:21], v[20:21], v[44:45], v[52:53]
	v_cvt_pk_bf16_f32 v18, v18, v19
	global_store_dwordx2 v32, v[30:31], s[16:17] sc1
	v_cvt_pk_bf16_f32 v19, v20, v21
	global_store_dwordx2 v32, v[18:19], s[10:11] sc1
	v_pk_mul_f32 v[18:19], v[26:27], v[84:85] op_sel_hi:[1,0]
	v_pk_mul_f32 v[20:21], v[28:29], v[84:85] op_sel_hi:[1,0]
	v_pk_fma_f32 v[18:19], v[18:19], v[42:43], v[50:51]
	v_pk_fma_f32 v[20:21], v[20:21], v[44:45], v[52:53]
	v_cvt_pk_bf16_f32 v18, v18, v19
	v_lshlrev_b32_e32 v26, 2, v87
	v_cvt_pk_bf16_f32 v19, v20, v21
	global_store_dwordx2 v32, v[18:19], s[12:13] sc1
	v_pk_mul_f32 v[18:19], v[22:23], v[86:87] op_sel_hi:[1,0]
	v_pk_mul_f32 v[20:21], v[24:25], v[86:87] op_sel_hi:[1,0]
	v_pk_fma_f32 v[18:19], v[18:19], v[42:43], v[50:51]
	v_pk_fma_f32 v[20:21], v[20:21], v[44:45], v[52:53]
	v_cvt_pk_bf16_f32 v18, v18, v19
	s_nop 0
	v_cvt_pk_bf16_f32 v19, v20, v21
	global_store_dwordx2 v32, v[18:19], s[14:15] sc1
	global_load_dwordx4 v[18:21], v[78:79], off offset:3072
	s_nop 0
	global_load_dwordx4 v[22:25], v26, s[2:3]
	s_nop 0
	global_load_dwordx4 v[26:29], v26, s[0:1]
	s_waitcnt vmcnt(1)
	v_pk_add_f32 v[24:25], v[24:25], 1.0 op_sel_hi:[1,0]
	v_pk_add_f32 v[22:23], v[22:23], 1.0 op_sel_hi:[1,0]
	v_pk_mul_f32 v[20:21], v[20:21], v[24:25]
	v_pk_mul_f32 v[18:19], v[18:19], v[22:23]
	s_waitcnt vmcnt(0)
	v_pk_fma_f32 v[16:17], v[16:17], v[20:21], v[28:29]
	v_pk_fma_f32 v[14:15], v[14:15], v[18:19], v[26:27]
	v_pk_fma_f32 v[2:3], v[2:3], v[18:19], v[26:27]
	v_cvt_pk_bf16_f32 v14, v14, v15
	v_cvt_pk_bf16_f32 v15, v16, v17
	v_lshlrev_b32_e32 v16, 1, v87
	v_pk_fma_f32 v[4:5], v[4:5], v[20:21], v[28:29]
	v_cvt_pk_bf16_f32 v2, v2, v3
	global_store_dwordx2 v16, v[14:15], s[16:17] sc1
	v_cvt_pk_bf16_f32 v3, v4, v5
	global_store_dwordx2 v16, v[2:3], s[10:11] sc1
	v_pk_mul_f32 v[2:3], v[10:11], v[84:85] op_sel_hi:[1,0]
	v_pk_mul_f32 v[4:5], v[12:13], v[84:85] op_sel_hi:[1,0]
	v_pk_fma_f32 v[2:3], v[2:3], v[18:19], v[26:27]
	v_pk_fma_f32 v[4:5], v[4:5], v[20:21], v[28:29]
	v_cvt_pk_bf16_f32 v2, v2, v3
	s_nop 0
	v_cvt_pk_bf16_f32 v3, v4, v5
	global_store_dwordx2 v16, v[2:3], s[12:13] sc1
	v_pk_mul_f32 v[2:3], v[6:7], v[86:87] op_sel_hi:[1,0]
	v_pk_mul_f32 v[4:5], v[8:9], v[86:87] op_sel_hi:[1,0]
	v_pk_fma_f32 v[2:3], v[2:3], v[18:19], v[26:27]
	v_pk_fma_f32 v[4:5], v[4:5], v[20:21], v[28:29]
	v_cvt_pk_bf16_f32 v2, v2, v3
	s_nop 0
	v_cvt_pk_bf16_f32 v3, v4, v5
	global_store_dwordx2 v16, v[2:3], s[14:15] sc1
	s_cbranch_scc0 .LBB0_615

; __device__ __forceinline__ unsigned pk2(float lo, float hi) { return cvtpk(lo, hi); }
; template <int NR>
; __device__ __forceinline__ void norm_group(int m0, const float* src_lat, const float* src_ctx, bf16* H, const float* gain, const float* mod, int shoff, int scoff, int lane, const float* part, float* ctx_out) {
;     ...
;     for (int i = 0; i < NR; ++i) { float s = 0.f;
; #pragma unroll
;         for (int j = 0; j < 4; ++j) s += (v[i][j].x * v[i][j].x + v[i][j].y * v[i][j].y) + (v[i][j].z * v[i][j].z + v[i][j].w * v[i][j].w);
;         rstd[i] = 1.0f / sqrtf(wave_sum(s) * (1.f / D) + EPS); }
;     const float* mr = mod + b * 6144;
; #pragma unroll
;     for (int j = 0; j < 4; ++j) { const int idx = 4 * (lane + 64 * j);
;         const f32x4 g = *(const f32x4*)(gain + idx), sc = *(const f32x4*)(mr + scoff + idx), sh = *(const f32x4*)(mr + shoff + idx);
;         const f32x4 gs = g * (1.f + sc);
; #pragma unroll
;         for (int i = 0; i < NR; ++i) { const f32x4 y = v[i][j] * rstd[i] * gs + sh;
;             v2u o; o.x = pk2(y.x, y.y); o.y = pk2(y.z, y.w);
;             *(v2u*)(H + (size_t)(m0 + i) * D + idx) = o; } }
; __device__ __forceinline__ void norm_pass(const float* src_lat, const float* src_ctx, bf16* H, const float* gain, const float* mod, int shoff, int scoff, int nrows, int lane, int wave, const float* part = nullptr, float* ctx_out = nullptr) {
;     ...
;     for (int m = MLAT + gw; m < nrows; m += NGW) norm_group<1>(m, src_lat, src_ctx, H, gain, mod, shoff, scoff, lane, part, ctx_out);
.LBB0_618:
	s_waitcnt vmcnt(3)
	v_pk_mul_f32 v[42:43], v[16:17], v[16:17]
	v_pk_mul_f32 v[44:45], v[14:15], v[14:15]
	s_waitcnt vmcnt(2)
	v_pk_mul_f32 v[30:31], v[12:13], v[12:13]
	v_pk_mul_f32 v[32:33], v[10:11], v[10:11]
	v_pk_mov_b32 v[46:47], v[44:45], v[42:43] op_sel:[1,0]
	v_mov_b32_e32 v45, v43
	v_pk_add_f32 v[42:43], v[46:47], v[44:45]
	v_pk_mov_b32 v[44:45], v[32:33], v[30:31] op_sel:[1,0]
	v_mov_b32_e32 v33, v31
	s_waitcnt vmcnt(1)
	v_mul_f32_e32 v22, v6, v6
	v_pk_add_f32 v[30:31], v[44:45], v[32:33]
	v_pk_fma_f32 v[32:33], v[6:7], v[6:7], v[22:23] op_sel_hi:[1,1,0]
	v_mul_f32_e32 v22, v8, v8
	v_pk_add_f32 v[42:43], v[42:43], v[42:43] op_sel_hi:[0,1]
	v_pk_add_f32 v[30:31], v[30:31], v[30:31] op_sel_hi:[0,1]
	v_pk_fma_f32 v[44:45], v[8:9], v[8:9], v[22:23] op_sel_hi:[1,1,0]
	s_waitcnt vmcnt(0)
	v_mul_f32_e32 v32, v2, v2
	v_mul_f32_e32 v44, v3, v3
	v_mul_f32_e32 v42, v4, v4
	v_mul_f32_e32 v30, v5, v5
	v_pk_add_f32 v[32:33], v[32:33], v[44:45]
	v_pk_add_f32 v[30:31], v[42:43], v[30:31]
	s_min_i32 s0, s6, 0x8000
	v_pk_add_f32 v[30:31], v[32:33], v[30:31]
	s_ashr_i32 s6, s0, 13
	v_add_f32_e32 v22, v30, v31
	ds_bpermute_b32 v29, v23, v22
	s_waitcnt lgkmcnt(0)
	v_add_f32_e32 v22, v22, v29
	ds_bpermute_b32 v29, v24, v22
	s_waitcnt lgkmcnt(0)
	v_add_f32_e32 v22, v22, v29
	ds_bpermute_b32 v29, v25, v22
	s_waitcnt lgkmcnt(0)
	v_add_f32_e32 v22, v22, v29
	ds_bpermute_b32 v29, v26, v22
	s_waitcnt lgkmcnt(0)
	v_add_f32_e32 v22, v22, v29
	ds_bpermute_b32 v29, v27, v22
	s_waitcnt lgkmcnt(0)
	v_add_f32_e32 v22, v22, v29
	ds_bpermute_b32 v29, v28, v22
	s_waitcnt lgkmcnt(0)
	v_add_f32_e32 v22, v22, v29
	v_fmamk_f32 v22, v22, 0x3a800000, v205
	v_cmp_gt_f32_e32 vcc, s88, v22
	v_mul_f32_e32 v29, 0x4f800000, v22
	s_nop 0
	v_cndmask_b32_e32 v22, v22, v29, vcc
	v_sqrt_f32_e32 v29, v22
	s_nop 0
	v_add_u32_e32 v30, -1, v29
	v_fma_f32 v31, -v30, v29, v22
	v_cmp_ge_f32_e64 s[0:1], 0, v31
	v_add_u32_e32 v31, 1, v29
	s_nop 0
	v_cndmask_b32_e64 v30, v29, v30, s[0:1]
	v_fma_f32 v29, -v31, v29, v22
	v_cmp_lt_f32_e64 s[0:1], 0, v29
	s_nop 1
	v_cndmask_b32_e64 v29, v30, v31, s[0:1]
	v_mul_f32_e32 v30, 0x37800000, v29
	v_cndmask_b32_e32 v29, v29, v30, vcc
	v_cmp_class_f32_e32 vcc, v22, v206
	s_nop 1
	v_cndmask_b32_e32 v22, v29, v22, vcc
	v_div_scale_f32 v29, s[0:1], v22, v22, 1.0
	v_rcp_f32_e32 v30, v29
	s_mul_i32 s0, s6, 0x1800
	s_ashr_i32 s1, s0, 31
	s_lshl_b64 s[0:1], s[0:1], 2
	v_fma_f32 v31, -v29, v30, 1.0
	v_fmac_f32_e32 v30, v31, v30
	v_div_scale_f32 v31, vcc, 1.0, v22, 1.0
	s_add_u32 s0, s72, s0
	v_mul_f32_e32 v32, v31, v30
	s_addc_u32 s1, s74, s1
	v_fma_f32 v33, -v29, v32, v31
	s_add_u32 s6, s0, 0x4000
	v_fmac_f32_e32 v32, v33, v30
	s_addc_u32 s7, s1, 0
	v_fma_f32 v29, -v29, v32, v31
	s_add_u32 s0, s0, 0x3000
	v_div_fmas_f32 v29, v29, v30, v32
	s_addc_u32 s1, s1, 0
	global_load_dwordx4 v[30:33], v[18:19], off
	global_load_dwordx4 v[42:45], v34, s[6:7]
	global_load_dwordx4 v[46:49], v34, s[0:1]
	v_div_fixup_f32 v22, v29, v22, 1.0
	v_pk_mul_f32 v[14:15], v[14:15], v[22:23] op_sel_hi:[1,0]
	v_pk_mul_f32 v[16:17], v[16:17], v[22:23] op_sel_hi:[1,0]
	v_lshlrev_b32_e32 v29, 2, v83
	v_pk_mul_f32 v[10:11], v[10:11], v[22:23] op_sel_hi:[1,0]
	v_pk_mul_f32 v[12:13], v[12:13], v[22:23] op_sel_hi:[1,0]
	v_pk_mul_f32 v[6:7], v[6:7], v[22:23] op_sel_hi:[1,0]
	v_pk_mul_f32 v[8:9], v[8:9], v[22:23] op_sel_hi:[1,0]
	s_add_i32 s78, s78, s52
	v_pk_mul_f32 v[2:3], v[2:3], v[22:23] op_sel_hi:[1,0]
	v_pk_mul_f32 v[4:5], v[4:5], v[22:23] op_sel_hi:[1,0]
	s_waitcnt vmcnt(1)
	v_pk_add_f32 v[42:43], v[42:43], 1.0 op_sel_hi:[1,0]
	v_pk_add_f32 v[44:45], v[44:45], 1.0 op_sel_hi:[1,0]
	v_pk_mul_f32 v[30:31], v[30:31], v[42:43]
	v_pk_mul_f32 v[32:33], v[32:33], v[44:45]
	s_waitcnt vmcnt(0)
	v_pk_fma_f32 v[14:15], v[30:31], v[14:15], v[46:47]
	v_pk_fma_f32 v[16:17], v[32:33], v[16:17], v[48:49]
	v_cvt_pk_bf16_f32 v14, v14, v15
	s_nop 0
	v_cvt_pk_bf16_f32 v15, v16, v17
	global_store_dwordx2 v[20:21], v[14:15], off sc1
	global_load_dwordx4 v[14:17], v[18:19], off offset:1024
	s_nop 0
	global_load_dwordx4 v[30:33], v29, s[6:7]
	global_load_dwordx4 v[42:45], v29, s[0:1]
	v_lshlrev_b32_e32 v29, 2, v85
	s_waitcnt vmcnt(1)
	v_pk_add_f32 v[30:31], v[30:31], 1.0 op_sel_hi:[1,0]
	v_pk_add_f32 v[32:33], v[32:33], 1.0 op_sel_hi:[1,0]
	v_pk_mul_f32 v[14:15], v[14:15], v[30:31]
	v_pk_mul_f32 v[16:17], v[16:17], v[32:33]
	s_waitcnt vmcnt(0)
	v_pk_fma_f32 v[10:11], v[14:15], v[10:11], v[42:43]
	v_pk_fma_f32 v[12:13], v[16:17], v[12:13], v[44:45]
	v_cvt_pk_bf16_f32 v10, v10, v11
	s_nop 0
	v_cvt_pk_bf16_f32 v11, v12, v13
	global_store_dwordx2 v[20:21], v[10:11], off offset:512 sc1
	global_load_dwordx4 v[10:13], v[18:19], off offset:2048
	s_nop 0
	global_load_dwordx4 v[14:17], v29, s[6:7]
	global_load_dwordx4 v[30:33], v29, s[0:1]
	s_waitcnt vmcnt(1)
	v_pk_add_f32 v[14:15], v[14:15], 1.0 op_sel_hi:[1,0]
	v_pk_add_f32 v[16:17], v[16:17], 1.0 op_sel_hi:[1,0]
	v_pk_mul_f32 v[10:11], v[10:11], v[14:15]
	v_pk_mul_f32 v[12:13], v[12:13], v[16:17]
	s_waitcnt vmcnt(0)
	v_pk_fma_f32 v[6:7], v[6:7], v[10:11], v[30:31]
	v_pk_fma_f32 v[8:9], v[8:9], v[12:13], v[32:33]
	v_cvt_pk_bf16_f32 v6, v6, v7
	v_lshlrev_b32_e32 v14, 2, v87
	v_cvt_pk_bf16_f32 v7, v8, v9
	global_store_dwordx2 v[20:21], v[6:7], off offset:1024 sc1
	global_load_dwordx4 v[6:9], v[18:19], off offset:3072
	s_nop 0
	global_load_dwordx4 v[10:13], v14, s[6:7]
	s_nop 0
	global_load_dwordx4 v[14:17], v14, s[0:1]
	s_add_i32 s0, s78, 0x8000
	s_add_u32 s2, s2, s52
	s_addc_u32 s3, s3, s53
	s_cmp_lt_i32 s0, s14
	s_waitcnt vmcnt(1)
	v_pk_add_f32 v[10:11], v[10:11], 1.0 op_sel_hi:[1,0]
	v_pk_add_f32 v[12:13], v[12:13], 1.0 op_sel_hi:[1,0]
	v_pk_mul_f32 v[6:7], v[6:7], v[10:11]
	v_pk_mul_f32 v[8:9], v[8:9], v[12:13]
	s_waitcnt vmcnt(0)
	v_pk_fma_f32 v[2:3], v[2:3], v[6:7], v[14:15]
	v_pk_fma_f32 v[4:5], v[4:5], v[8:9], v[16:17]
	v_cvt_pk_bf16_f32 v2, v2, v3
	s_nop 0
	v_cvt_pk_bf16_f32 v3, v4, v5
	global_store_dwordx2 v[20:21], v[2:3], off offset:1536 sc1
	v_lshl_add_u64 v[20:21], v[20:21], 0, s[66:67]
	s_cbranch_scc0 .LBB0_623

; template <int NR>
; __device__ __forceinline__ void norm_group(int m0, const float* src_lat, const float* src_ctx, bf16* H, const float* gain, const float* mod, int shoff, int scoff, int lane, const float* part, float* ctx_out) {
;     ...
;     if (part && m0 >= MLAT) {
; #pragma unroll
;         for (int i = 0; i < NR; ++i)
; #pragma unroll
;             for (int j = 0; j < 4; ++j) { const size_t o = (size_t)(m0 - MLAT + i) * D + 4 * (lane + 64 * j);
;                 const f32x4 p0 = *(const f32x4*)(part + o), p1 = *(const f32x4*)(part + (size_t)MCTX * D + o), p2 = *(const f32x4*)(part + (size_t)2 * MCTX * D + o), p3 = *(const f32x4*)(part + (size_t)3 * MCTX * D + o);
;                 v[i][j] = v[i][j] + ((p0 + p1) + (p2 + p3)); *(f32x4*)(ctx_out + o) = v[i][j]; }
;     }
.LBB0_621:
	s_andn2_b64 vcc, exec, s[0:1]
	s_cbranch_vccnz .LBB0_618
	s_lshl_b64 s[0:1], s[78:79], 10
	v_mov_b32_e32 v31, s1
	v_or_b32_e32 v30, s0, v81
	v_lshlrev_b64 v[54:55], 2, v[30:31]
	v_lshl_add_u64 v[30:31], s[50:51], 0, v[54:55]
	v_lshl_add_u64 v[42:43], s[8:9], 0, v[54:55]
	v_lshl_add_u64 v[46:47], s[10:11], 0, v[54:55]
	v_lshl_add_u64 v[50:51], s[12:13], 0, v[54:55]
	global_load_dwordx4 v[30:33], v[30:31], off
	s_nop 0
	global_load_dwordx4 v[42:45], v[42:43], off
	s_nop 0
	global_load_dwordx4 v[46:49], v[46:47], off
	s_waitcnt vmcnt(1)
	v_pk_add_f32 v[32:33], v[32:33], v[44:45]
	global_load_dwordx4 v[50:53], v[50:51], off
	v_pk_add_f32 v[30:31], v[30:31], v[42:43]
	s_waitcnt vmcnt(0)
	v_pk_add_f32 v[42:43], v[48:49], v[52:53]
	v_pk_add_f32 v[44:45], v[46:47], v[50:51]
	v_pk_add_f32 v[32:33], v[32:33], v[42:43]
	v_pk_add_f32 v[30:31], v[30:31], v[44:45]
	v_pk_add_f32 v[16:17], v[16:17], v[32:33]
	v_pk_add_f32 v[14:15], v[14:15], v[30:31]
	v_lshl_add_u64 v[30:31], s[94:95], 0, v[54:55]
	global_store_dwordx4 v[30:31], v[14:17], off sc1
	v_mov_b32_e32 v31, s1
	v_or_b32_e32 v30, s0, v83
	v_lshlrev_b64 v[54:55], 2, v[30:31]
	v_lshl_add_u64 v[30:31], s[50:51], 0, v[54:55]
	v_lshl_add_u64 v[42:43], s[8:9], 0, v[54:55]
	v_lshl_add_u64 v[46:47], s[10:11], 0, v[54:55]
	v_lshl_add_u64 v[50:51], s[12:13], 0, v[54:55]
	global_load_dwordx4 v[30:33], v[30:31], off
	s_nop 0
	global_load_dwordx4 v[42:45], v[42:43], off
	s_nop 0
	global_load_dwordx4 v[46:49], v[46:47], off
	s_waitcnt vmcnt(1)
	v_pk_add_f32 v[32:33], v[32:33], v[44:45]
	global_load_dwordx4 v[50:53], v[50:51], off
	v_pk_add_f32 v[30:31], v[30:31], v[42:43]
	s_waitcnt vmcnt(0)
	v_pk_add_f32 v[42:43], v[48:49], v[52:53]
	v_pk_add_f32 v[44:45], v[46:47], v[50:51]
	v_pk_add_f32 v[32:33], v[32:33], v[42:43]
	v_pk_add_f32 v[30:31], v[30:31], v[44:45]
	v_pk_add_f32 v[12:13], v[12:13], v[32:33]
	v_pk_add_f32 v[10:11], v[10:11], v[30:31]
	v_lshl_add_u64 v[30:31], s[94:95], 0, v[54:55]
	global_store_dwordx4 v[30:31], v[10:13], off sc1
	v_mov_b32_e32 v31, s1
	v_or_b32_e32 v30, s0, v85
	v_lshlrev_b64 v[54:55], 2, v[30:31]
	v_lshl_add_u64 v[30:31], s[50:51], 0, v[54:55]
	v_lshl_add_u64 v[42:43], s[8:9], 0, v[54:55]
	v_lshl_add_u64 v[46:47], s[10:11], 0, v[54:55]
	v_lshl_add_u64 v[50:51], s[12:13], 0, v[54:55]
	global_load_dwordx4 v[30:33], v[30:31], off
	s_nop 0
	global_load_dwordx4 v[42:45], v[42:43], off
	s_nop 0
	global_load_dwordx4 v[46:49], v[46:47], off
	s_waitcnt vmcnt(1)
	v_pk_add_f32 v[32:33], v[32:33], v[44:45]
	global_load_dwordx4 v[50:53], v[50:51], off
	v_pk_add_f32 v[30:31], v[30:31], v[42:43]
	s_waitcnt vmcnt(0)
	v_pk_add_f32 v[42:43], v[48:49], v[52:53]
	v_pk_add_f32 v[44:45], v[46:47], v[50:51]
	v_pk_add_f32 v[32:33], v[32:33], v[42:43]
	v_pk_add_f32 v[30:31], v[30:31], v[44:45]
	v_pk_add_f32 v[8:9], v[8:9], v[32:33]
	v_pk_add_f32 v[6:7], v[6:7], v[30:31]
	v_lshl_add_u64 v[30:31], s[94:95], 0, v[54:55]
	global_store_dwordx4 v[30:31], v[6:9], off sc1
	v_mov_b32_e32 v31, s1
	v_or_b32_e32 v30, s0, v87
	v_lshlrev_b64 v[54:55], 2, v[30:31]
	v_lshl_add_u64 v[30:31], s[50:51], 0, v[54:55]
	v_lshl_add_u64 v[42:43], s[8:9], 0, v[54:55]
	v_lshl_add_u64 v[46:47], s[10:11], 0, v[54:55]
	v_lshl_add_u64 v[50:51], s[12:13], 0, v[54:55]
	global_load_dwordx4 v[30:33], v[30:31], off
	s_nop 0
	global_load_dwordx4 v[42:45], v[42:43], off
	s_nop 0
	global_load_dwordx4 v[46:49], v[46:47], off
	s_waitcnt vmcnt(1)
	v_pk_add_f32 v[32:33], v[32:33], v[44:45]
	global_load_dwordx4 v[50:53], v[50:51], off
	v_pk_add_f32 v[30:31], v[30:31], v[42:43]
	s_waitcnt vmcnt(0)
	v_pk_add_f32 v[42:43], v[48:49], v[52:53]
	v_pk_add_f32 v[44:45], v[46:47], v[50:51]
	v_pk_add_f32 v[32:33], v[32:33], v[42:43]
	v_pk_add_f32 v[30:31], v[30:31], v[44:45]
	v_pk_add_f32 v[4:5], v[4:5], v[32:33]
	v_pk_add_f32 v[2:3], v[2:3], v[30:31]
	v_lshl_add_u64 v[30:31], s[94:95], 0, v[54:55]
	global_store_dwordx4 v[30:31], v[2:5], off sc1
	s_branch .LBB0_618
